# pool sample-unit slab build batched (4+2 rows in flight), LRU sample conv-build loads batched, early-LN gamma/beta hoisted, G1 bias wait inside the conditional
# baseline (speedup 1.0000x reference)
; __device__ __forceinline__ float fast_sigmoid(float v) { return __builtin_amdgcn_rcpf(1.0f + __expf(-v)); }
;     __device__ __forceinline__ void operator()(const f32x4 (&acc)[2][2][4][2], const Unit& u, int wr, int wc, int fr, int fq) const {
;     ...
;         const int mode = (u.pn >= 24) ? 2 : (((u.pn >= 4 && u.pn < 8) || (u.pn >= 16)) ? 1 : 0);
;         f32x4 bv[2][2];
; #pragma unroll
;         for (int bj = 0; bj < 2; ++bj)
; #pragma unroll
;             for (int n = 0; n < 2; ++n) bv[bj][n] = (mode == 2) ? *(const f32x4*)(bmerge + (col0 - 6144) + bj * HALF + 4 * n) : (f32x4){0.f, 0.f, 0.f, 0.f};
; #pragma unroll
;         for (int ai = 0; ai < 2; ++ai)
; #pragma unroll
;             for (int m = 0; m < 4; ++m) { bf16_t* rowp = O + (size_t)(row0 + ai * HALF + m * 16) * ldc + col0;
; #pragma unroll
;                 for (int bj = 0; bj < 2; ++bj) { f32x4 v0 = acc[ai][bj][m][0] + bv[bj][0], v1 = acc[ai][bj][m][1] + bv[bj][1];
;                     if (mode == 1) {
; #pragma unroll
;                         for (int j = 0; j < 4; ++j) { v0[j] = v0[j] * fast_sigmoid(v0[j]); v1[j] = v1[j] * fast_sigmoid(v1[j]); } }
;                     else if (mode == 2) {
; #pragma unroll
;                         for (int j = 0; j < 4; ++j) { v0[j] = fast_sigmoid(v0[j]); v1[j] = fast_sigmoid(v1[j]); } }
.LBB0_169:
	s_and_b32 s2, s52, -4
	s_cmp_eq_u32 s2, 4
	s_cselect_b64 s[2:3], -1, 0
	s_cmp_gt_i32 s52, 15
	s_cselect_b64 s[6:7], -1, 0
	s_or_b64 s[2:3], s[6:7], s[2:3]
	v_cndmask_b32_e64 v27, 0, 1, s[2:3]
	s_and_b64 vcc, exec, s[0:1]
	v_readfirstlane_b32 s20, v27
	v_mov_b32_e32 v27, 0
	v_mov_b32_e32 v28, 0
	v_mov_b32_e32 v29, 0
	s_cbranch_vccnz .LBB0_171
	v_add_co_u32_e32 v26, vcc, 0xffffb000, v158
	s_mov_b32 s20, 2
	s_nop 0
	v_addc_co_u32_e32 v27, vcc, -1, v159, vcc
	global_load_dwordx4 v[26:29], v[26:27], off offset:-3568
	s_waitcnt vmcnt(0)
.LBB0_171:
	v_pk_add_f32 v[144:145], v[144:145], v[48:49]
	v_pk_add_f32 v[142:143], v[142:143], v[46:47]
	v_pk_add_f32 v[140:141], v[140:141], v[44:45]
	v_pk_add_f32 v[138:139], v[138:139], v[42:43]
	s_cmp_gt_i32 s20, 1
	s_mov_b64 s[0:1], -1
	s_cbranch_scc0 .LBB0_173
	v_mul_f32_e32 v157, 0xbfb8aa3b, v142
	v_exp_f32_e32 v157, v157
	v_mul_f32_e32 v158, 0xbfb8aa3b, v138
	v_exp_f32_e32 v158, v158
	v_mul_f32_e32 v168, 0xbfb8aa3b, v139
	v_add_f32_e32 v157, 1.0, v157
	v_exp_f32_e32 v169, v168
	v_add_f32_e32 v159, 1.0, v158
	v_rcp_f32_e32 v158, v157
	v_mul_f32_e32 v157, 0xbfb8aa3b, v143
	v_exp_f32_e32 v157, v157
	v_rcp_f32_e32 v159, v159
	s_mov_b64 s[0:1], 0
	v_add_f32_e32 v157, 1.0, v157
	v_rcp_f32_e32 v168, v157
	v_add_f32_e32 v157, 1.0, v169
	v_mul_f32_e32 v169, 0xbfb8aa3b, v144
	v_exp_f32_e32 v170, v169
	v_mul_f32_e32 v169, 0xbfb8aa3b, v140
	v_exp_f32_e32 v171, v169
	v_rcp_f32_e32 v169, v157
	v_add_f32_e32 v157, 1.0, v170
	v_rcp_f32_e32 v170, v157
	v_add_f32_e32 v157, 1.0, v171
	v_mul_f32_e32 v171, 0xbfb8aa3b, v145
	v_exp_f32_e32 v172, v171
	v_mul_f32_e32 v171, 0xbfb8aa3b, v141
	v_exp_f32_e32 v174, v171
	v_rcp_f32_e32 v171, v157
	v_add_f32_e32 v157, 1.0, v172
	v_rcp_f32_e32 v173, v157
	v_add_f32_e32 v157, 1.0, v174
	v_rcp_f32_e32 v172, v157

; #define LAS __attribute__((address_space(3)))
; __device__ __forceinline__ unsigned pk2(float lo, float hi) { return f2bf(lo) | (f2bf(hi) << 16); }
; #define BF8_TO_F32(vw, lo, hi) const f32x4 lo = {bflo(vw.x), bfhi(vw.x), bflo(vw.y), bfhi(vw.y)}, hi = {bflo(vw.z), bfhi(vw.z), bflo(vw.w), bfhi(vw.w)}
; __device__ __forceinline__ void mix_phase(LAS unsigned char* lds, const Params& p, const int layer) {
;     ...
;                 for (int i = 0; i < 2; ++i) {
;                     const int rl = (tid >> 4) + 32 * i, r = r0N + rl, c = c0 + q16 * 8, t = (r - NP) & 7, bs = (r - NP) >> 3;
;                     f32x4 x0 = *(const LAS f32x4*)(CWL + q16 * 8), x1 = *(const LAS f32x4*)(CWL + q16 * 8 + 4);
; #pragma unroll
;                     for (int k = 0; k < 4; ++k) { const int jb = 3 - k;
;                         const f32x4 w0 = *(const LAS f32x4*)(CWL + (k + 1) * 128 + q16 * 8), w1 = *(const LAS f32x4*)(CWL + (k + 1) * 128 + q16 * 8 + 4);
;                         if (jb <= t) { const v4u vw = *(const v4u*)(PROJ + (size_t)(r - jb) * NC + C_UB + c); BF8_TO_F32(vw, a0, a1); x0 += w0 * a0; x1 += w1 * a1; }
;                         else { const float* sp = sconv + ((size_t)bs * 3 + (3 + t - jb)) * LW + c; x0 += w0 * *(const f32x4*)sp; x1 += w1 * *(const f32x4*)(sp + 4); }
;                     }
;                     *(LAS f32x4*)(XCN + rl * 132 + q16 * 8) = x0; *(LAS f32x4*)(XCN + rl * 132 + q16 * 8 + 4) = x1;
;                     v4u o; o.x = pk2(x0[0], x0[1]); o.y = pk2(x0[2], x0[3]); o.z = pk2(x1[0], x1[1]); o.w = pk2(x1[2], x1[3]);
;                     *(LAS v4u*)(AtN + rl * 136 + q16 * 8) = o;
;                 }
.LBB0_490:
	s_or_b64 exec, exec, s[50:51]
	s_waitcnt lgkmcnt(0)
	s_and_saveexec_b64 s[20:21], s[44:45]
	s_waitcnt vmcnt(0)
	v_lshlrev_b32_e32 v90, 16, v94
	v_and_b32_e32 v91, 0xffff0000, v94
	v_lshlrev_b32_e32 v92, 16, v95
	v_and_b32_e32 v93, 0xffff0000, v95
	v_lshlrev_b32_e32 v94, 16, v96
	v_and_b32_e32 v95, 0xffff0000, v96
	v_lshlrev_b32_e32 v96, 16, v97
	v_and_b32_e32 v97, 0xffff0000, v97
	s_mov_b64 exec, s[20:21]
	s_and_saveexec_b64 s[20:21], s[46:47]
	v_lshlrev_b32_e32 v106, 16, v110
	v_and_b32_e32 v107, 0xffff0000, v110
	v_lshlrev_b32_e32 v108, 16, v111
	v_and_b32_e32 v109, 0xffff0000, v111
	v_lshlrev_b32_e32 v110, 16, v112
	v_and_b32_e32 v111, 0xffff0000, v112
	v_lshlrev_b32_e32 v112, 16, v113
	v_and_b32_e32 v113, 0xffff0000, v113
	s_mov_b64 exec, s[20:21]
	s_and_saveexec_b64 s[20:21], s[48:49]
	v_lshlrev_b32_e32 v122, 16, v126
	v_and_b32_e32 v123, 0xffff0000, v126
	v_lshlrev_b32_e32 v124, 16, v127
	v_and_b32_e32 v125, 0xffff0000, v127
	v_lshlrev_b32_e32 v126, 16, v128
	v_and_b32_e32 v127, 0xffff0000, v128
	v_lshlrev_b32_e32 v128, 16, v129
	v_and_b32_e32 v129, 0xffff0000, v129
	s_mov_b64 exec, s[20:21]
	v_pk_fma_f32 v[74:75], v[82:83], v[94:95], v[74:75]
	v_mov_b64_e32 v[82:83], s[74:75]
	s_xor_b64 s[86:87], s[0:1], -1
	v_mad_i64_i32 v[82:83], s[0:1], v171, s25, v[82:83]
	v_lshl_add_u64 v[82:83], v[82:83], 0, v[0:1]
	s_movk_i32 s0, 0x1000
	v_pk_fma_f32 v[80:81], v[88:89], v[92:93], v[80:81]
	v_pk_fma_f32 v[78:79], v[86:87], v[90:91], v[78:79]
	v_pk_fma_f32 v[76:77], v[84:85], v[96:97], v[76:77]
	v_add_co_u32_e32 v82, vcc, s0, v82
	v_pk_fma_f32 v[80:81], v[104:105], v[108:109], v[80:81]
	v_pk_fma_f32 v[78:79], v[102:103], v[106:107], v[78:79]
	v_pk_fma_f32 v[76:77], v[100:101], v[112:113], v[76:77]
	v_pk_fma_f32 v[74:75], v[98:99], v[110:111], v[74:75]
	v_addc_co_u32_e32 v83, vcc, 0, v83, vcc
	v_pk_fma_f32 v[86:87], v[120:121], v[124:125], v[80:81]
	v_pk_fma_f32 v[88:89], v[118:119], v[122:123], v[78:79]
	v_pk_fma_f32 v[90:91], v[116:117], v[128:129], v[76:77]
	v_pk_fma_f32 v[92:93], v[114:115], v[126:127], v[74:75]
	ds_read_b128 v[74:77], v233 offset:2048
	ds_read_b128 v[78:81], v233 offset:2064
	global_load_dwordx4 v[82:85], v[82:83], off
	s_movk_i32 s0, 0x210
	s_mov_b32 s17, 32
	s_andn2_b64 vcc, exec, s[86:87]
	s_waitcnt lgkmcnt(0)
	s_waitcnt vmcnt(0)
	v_lshlrev_b32_e32 v96, 16, v82
	v_and_b32_e32 v97, 0xffff0000, v82
	v_lshlrev_b32_e32 v82, 16, v83
	v_and_b32_e32 v83, 0xffff0000, v83
	v_pk_fma_f32 v[74:75], v[74:75], v[96:97], v[88:89]
	v_lshlrev_b32_e32 v94, 16, v84
	v_and_b32_e32 v95, 0xffff0000, v84
	v_lshlrev_b32_e32 v84, 16, v85
	v_and_b32_e32 v85, 0xffff0000, v85
	v_pk_fma_f32 v[76:77], v[76:77], v[82:83], v[86:87]
	v_mad_u64_u32 v[82:83], s[0:1], v159, s0, v[198:199]
	v_bfe_u32 v0, v74, 16, 1
	v_pk_fma_f32 v[80:81], v[80:81], v[84:85], v[90:91]
	v_pk_fma_f32 v[78:79], v[78:79], v[94:95], v[92:93]
	ds_write_b128 v82, v[74:77]
	ds_write_b128 v82, v[78:81] offset:16
	v_add3_u32 v0, v74, v0, s26
	v_bfe_u32 v74, v75, 16, 1
	v_lshrrev_b32_e32 v0, 16, v0
	v_add3_u32 v74, v75, v74, s26
	v_and_or_b32 v74, v74, s24, v0
	v_bfe_u32 v0, v76, 16, 1
	v_add3_u32 v0, v76, v0, s26
	v_bfe_u32 v75, v77, 16, 1
	v_lshrrev_b32_e32 v0, 16, v0
	v_add3_u32 v75, v77, v75, s26
	v_and_or_b32 v75, v75, s24, v0
	v_bfe_u32 v0, v78, 16, 1
	v_add3_u32 v0, v78, v0, s26
	v_bfe_u32 v76, v79, 16, 1
	v_lshrrev_b32_e32 v0, 16, v0
	v_add3_u32 v76, v79, v76, s26
	v_and_or_b32 v76, v76, s24, v0
	v_bfe_u32 v0, v80, 16, 1
	v_add3_u32 v0, v80, v0, s26
	v_bfe_u32 v77, v81, 16, 1
	s_movk_i32 s0, 0x110
	v_lshrrev_b32_e32 v0, 16, v0
	v_add3_u32 v77, v81, v77, s26
	v_mad_u64_u32 v[78:79], s[0:1], v159, s0, v[208:209]
	v_and_or_b32 v77, v77, s24, v0
	s_mov_b64 s[0:1], 0
	ds_write_b128 v78, v[74:77]
	s_cbranch_vccz .LBB0_503
.LBB0_491:
	ds_read_b128 v[78:81], v233
	ds_read_b128 v[74:77], v233 offset:16
	ds_read_b128 v[86:89], v233 offset:512
	ds_read_b128 v[82:85], v233 offset:528
	v_add_u32_e32 v159, s17, v226
	v_add_u32_e32 v171, s16, v159
	v_lshlrev_b32_e32 v0, 1, v136
	s_and_saveexec_b64 s[20:21], s[44:45]
	s_xor_b64 s[50:51], exec, s[20:21]
	s_cbranch_execz .LBB0_493
	v_add_u32_e32 v92, -3, v171
	v_mov_b64_e32 v[90:91], s[74:75]
	v_mad_i64_i32 v[90:91], s[20:21], v92, s25, v[90:91]
	v_lshl_add_u64 v[90:91], v[90:91], 0, v[0:1]
	v_add_co_u32_e32 v90, vcc, 0x1000, v90
	s_nop 1
	v_addc_co_u32_e32 v91, vcc, 0, v91, vcc
	global_load_dwordx4 v[94:97], v[90:91], off
.LBB0_493:
	s_or_saveexec_b64 s[50:51], s[50:51]
	v_add_u32_e32 v98, 0xffffe000, v171
	v_ashrrev_i32_e32 v98, 3, v98
	v_lshl_add_u32 v214, v98, 1, v98
	v_ashrrev_i32_e32 v215, 31, v214
	s_xor_b64 exec, exec, s[50:51]
	s_cbranch_execz .LBB0_495
	v_lshl_add_u64 v[90:91], v[214:215], 0, v[210:211]
	v_lshlrev_b64 v[90:91], 13, v[90:91]
	v_lshl_add_u64 v[90:91], v[148:149], 0, v[90:91]
	global_load_dwordx4 v[94:97], v[90:91], off offset:16
	s_nop 0
	global_load_dwordx4 v[90:93], v[90:91], off
.LBB0_495:
	s_or_b64 exec, exec, s[50:51]
	ds_read_b128 v[102:105], v233 offset:1024
	ds_read_b128 v[98:101], v233 offset:1040
	s_and_saveexec_b64 s[20:21], s[46:47]
	s_xor_b64 s[50:51], exec, s[20:21]
	s_cbranch_execz .LBB0_497
	v_add_u32_e32 v108, -2, v171
	v_mov_b64_e32 v[106:107], s[74:75]
	v_mad_i64_i32 v[106:107], s[20:21], v108, s25, v[106:107]
	v_lshl_add_u64 v[106:107], v[106:107], 0, v[0:1]
	v_add_co_u32_e32 v106, vcc, 0x1000, v106
	s_nop 1
	v_addc_co_u32_e32 v107, vcc, 0, v107, vcc
	global_load_dwordx4 v[110:113], v[106:107], off
.LBB0_497:
	s_andn2_saveexec_b64 s[20:21], s[50:51]
	s_cbranch_execz .LBB0_499
	v_lshl_add_u64 v[106:107], v[214:215], 0, v[212:213]
	v_lshlrev_b64 v[106:107], 13, v[106:107]
	v_lshl_add_u64 v[106:107], v[148:149], 0, v[106:107]
	global_load_dwordx4 v[110:113], v[106:107], off offset:16
	s_nop 0
	global_load_dwordx4 v[106:109], v[106:107], off

; #define LAS __attribute__((address_space(3)))
; #define BF8_TO_F32(vw, lo, hi) const f32x4 lo = {bflo(vw.x), bfhi(vw.x), bflo(vw.y), bfhi(vw.y)}, hi = {bflo(vw.z), bfhi(vw.z), bflo(vw.w), bfhi(vw.w)}
; __device__ __forceinline__ void mix_phase(LAS unsigned char* lds, const Params& p, const int layer) {
;     ...
;                     for (int k = 0; k < 4; ++k) { const int jb = 3 - k;
;                         const f32x4 w0 = *(const LAS f32x4*)(CWL + (k + 1) * 128 + q16 * 8), w1 = *(const LAS f32x4*)(CWL + (k + 1) * 128 + q16 * 8 + 4);
;                         if (jb <= t) { const v4u vw = *(const v4u*)(PROJ + (size_t)(r - jb) * NC + C_UB + c); BF8_TO_F32(vw, a0, a1); x0 += w0 * a0; x1 += w1 * a1; }
;                         else { const float* sp = sconv + ((size_t)bs * 3 + (3 + t - jb)) * LW + c; x0 += w0 * *(const f32x4*)sp; x1 += w1 * *(const f32x4*)(sp + 4); }
.LBB0_501:
	s_andn2_saveexec_b64 s[50:51], s[50:51]
	s_cbranch_execz .LBB0_490
	v_lshlrev_b64 v[122:123], 13, v[214:215]
	v_lshl_add_u64 v[122:123], v[148:149], 0, v[122:123]
	s_mov_b64 s[20:21], 0x4000
	v_lshl_add_u64 v[254:255], v[122:123], 0, s[20:21]
	v_add_co_u32_e32 v122, vcc, 0x4000, v122
	s_nop 1
	v_addc_co_u32_e32 v123, vcc, 0, v123, vcc
	global_load_dwordx4 v[122:125], v[122:123], off
	s_nop 0
	global_load_dwordx4 v[126:129], v[254:255], off offset:16
	s_branch .LBB0_490

; #define LAS __attribute__((address_space(3)))
; #define BF8_TO_F32(vw, lo, hi) const f32x4 lo = {bflo(vw.x), bfhi(vw.x), bflo(vw.y), bfhi(vw.y)}, hi = {bflo(vw.z), bfhi(vw.z), bflo(vw.w), bfhi(vw.w)}
; __device__ __forceinline__ void mix_phase(LAS unsigned char* lds, const Params& p, const int layer) {
;     ...
;         for (; ua < NUA; ua += G) {
;             const int tt = ua >> 2, g = ua & 3, r0 = tt * 32, w = 2 << g;
;             const bool prt = r0 < NP;
;             const int col = g * 256 + q * 8;
;             __syncthreads();
;             if (g != g_cur) { g_cur = g;
;                 const bf16* WT = (const bf16*)(ws + WS_POOLW) + (size_t)(layer * 4 + g) * 65536 + (size_t)(wid * 32 + fr) * 256 + fq * 8;
; #pragma unroll
;                 for (int n = 0; n < 2; ++n)
; #pragma unroll
;                     for (int ks = 0; ks < 8; ++ks) b[n][ks] = *(const bf16x8*)(WT + (size_t)n * 16 * 256 + ks * 32);
; #pragma unroll
;                 for (int n = 0; n < 2; ++n) ps[n] = *(const f32x4*)(p.in[8] + layer * PW + g * 256 + wid * 32 + n * 16 + fq * 4); }
;             if (prt) {
;                 const int t0 = r0 & 2047;
; #pragma unroll
;                 for (int k = 0; k < 3; ++k) { const int i = i0 + 16 * k; const float f = ((i < 47) && (t0 - 15 + i >= 0)) ? 1.0f : 0.0f; BF8_TO_F32(vw[k], a0, a1);
;                     if (i < 47) { *(LAS f32x4*)(SL + i * 264 + q * 8) = a0 * f; *(LAS f32x4*)(SL + i * 264 + q * 8 + 4) = a1 * f; } }
;             } else {
;                 const float* spool = p.in[2] + (size_t)layer * 128 * 15 * PW; const int bs0 = (r0 - NP) >> 3;
; #pragma unroll 2
;                 for (int i = tid >> 5; i < 92; i += 16) { const int sq = i / 23, ii = i - sq * 23; f32x4 a0, a1;
;                     if (ii < 15) { const float* sp = spool + ((size_t)(bs0 + sq) * 15 + ii) * PW + col; a0 = *(const f32x4*)sp; a1 = *(const f32x4*)(sp + 4); }
;                     else { const v4u vv = *(const v4u*)(PROJ + (size_t)(NP + (bs0 + sq) * 8 + (ii - 15)) * NC + C_UA + col); BF8_TO_F32(vv, c0_, c1_); a0 = c0_; a1 = c1_; }
;                     *(LAS f32x4*)(SL + i * 264 + q * 8) = a0; *(LAS f32x4*)(SL + i * 264 + q * 8 + 4) = a1; }
;             }
.LBB0_551:
	s_and_b32 s12, s3, 3
	s_lshl_b32 s6, s12, 8
	s_cmp_eq_u32 s12, s5
	s_waitcnt lgkmcnt(0)
	s_barrier
	s_cbranch_scc1 .LBB0_553
	s_lshl_b32 s5, s34, 1
	s_lshl_b32 s7, s12, 17
	s_or_b32 s14, s7, s5
	s_mov_b32 s15, s80
	s_waitcnt vmcnt(10)
	v_lshl_add_u64 v[46:47], v[110:111], 0, s[14:15]
	global_load_dwordx4 v[42:45], v[46:47], off
	global_load_dwordx4 v[38:41], v[46:47], off offset:64
	global_load_dwordx4 v[34:37], v[46:47], off offset:128
	global_load_dwordx4 v[30:33], v[46:47], off offset:192
	global_load_dwordx4 v[26:29], v[46:47], off offset:256
	global_load_dwordx4 v[22:25], v[46:47], off offset:320
	global_load_dwordx4 v[18:21], v[46:47], off offset:384
	global_load_dwordx4 v[14:17], v[46:47], off offset:448
	v_add_co_u32_e32 v46, vcc, 0x2000, v46
	s_lshl_b32 s14, s6, 2
	s_nop 0
	v_addc_co_u32_e32 v47, vcc, 0, v47, vcc
	global_load_dwordx4 v[74:77], v[46:47], off
	global_load_dwordx4 v[70:73], v[46:47], off offset:64
	global_load_dwordx4 v[66:69], v[46:47], off offset:128
	global_load_dwordx4 v[62:65], v[46:47], off offset:192
	global_load_dwordx4 v[58:61], v[46:47], off offset:256
	global_load_dwordx4 v[54:57], v[46:47], off offset:320
	global_load_dwordx4 v[50:53], v[46:47], off offset:384
	s_nop 0
	global_load_dwordx4 v[46:49], v[46:47], off offset:448
	v_lshl_add_u64 v[78:79], v[116:117], 0, s[14:15]
	global_load_dwordx4 v[82:85], v[78:79], off
	s_nop 0
	global_load_dwordx4 v[78:81], v[78:79], off offset:64
	s_mov_b32 s5, s12
	s_waitcnt vmcnt(0)
.LBB0_553:
	s_lshl_b32 s13, s3, 3
	s_and_b32 s7, s13, 0xffffffe0
	s_cmpk_lt_i32 s7, 0x2000
	s_cselect_b64 s[52:53], -1, 0
	s_cmpk_gt_i32 s7, 0x1fff
	s_mov_b64 s[20:21], -1
	s_cbranch_scc0 .LBB0_573
	s_and_saveexec_b64 s[48:49], s[38:39]
	s_cbranch_execz .LBB0_572
	s_add_i32 s14, s7, 0xffffe000
	v_or_b32_e32 v0, s6, v133
	s_lshr_b32 s14, s14, 3
	v_lshl_add_u64 v[94:95], v[0:1], 1, s[74:75]
	v_lshl_add_u64 v[96:97], v[0:1], 2, s[0:1]
	s_mov_b64 s[16:17], exec
	v_mul_lo_u32 v98, v121, s19
	v_add_u32_e32 v98, v98, v120
	v_add_u32_e32 v161, 0x10800, v98
	v_mov_b32_e32 v0, v121
	v_mul_u32_u24_e32 v99, 0xb22, v0
	v_lshrrev_b32_e32 v99, 16, v99
	v_mul_u32_u24_e32 v100, 23, v99
	v_sub_u32_e32 v100, v0, v100
	v_cmp_lt_i32_e32 vcc, 14, v100
	s_and_b64 s[20:21], s[16:17], vcc
	s_mov_b64 exec, s[20:21]
	v_mul_u32_u24_e32 v101, 15, v99
	v_sub_u32_e32 v101, v0, v101
	v_add_u32_e32 v101, s7, v101
	v_add_u32_e32 v101, -15, v101
	v_mad_i64_i32 v[150:151], vcc, v101, s25, v[94:95]
	global_load_dwordx4 v[6:9], v[150:151], off
	s_andn2_b64 exec, s[16:17], s[20:21]
	v_add_u32_e32 v101, s14, v99
	v_mul_u32_u24_e32 v101, 15, v101
	v_add_u32_e32 v150, v101, v100
	v_lshlrev_b32_e32 v150, 12, v150
	v_mov_b32_e32 v151, 0
	v_lshl_add_u64 v[150:151], v[96:97], 0, v[150:151]
	global_load_dwordx4 v[6:9], v[150:151], off offset:16
	global_load_dwordx4 v[2:5], v[150:151], off
	s_mov_b64 exec, s[16:17]
	v_add_u32_e32 v0, 16, v121
	v_mul_u32_u24_e32 v99, 0xb22, v0
	v_lshrrev_b32_e32 v99, 16, v99
	v_mul_u32_u24_e32 v100, 23, v99
	v_sub_u32_e32 v100, v0, v100
	v_cmp_lt_i32_e32 vcc, 14, v100
	s_and_b64 s[90:91], s[16:17], vcc
	s_mov_b64 exec, s[90:91]
	v_mul_u32_u24_e32 v101, 15, v99
	v_sub_u32_e32 v101, v0, v101
	v_add_u32_e32 v101, s7, v101
	v_add_u32_e32 v101, -15, v101
	v_mad_i64_i32 v[150:151], vcc, v101, s25, v[94:95]
	global_load_dwordx4 v[86:89], v[150:151], off
	s_andn2_b64 exec, s[16:17], s[90:91]
	v_add_u32_e32 v101, s14, v99
	v_mul_u32_u24_e32 v101, 15, v101
	v_add_u32_e32 v150, v101, v100
	v_lshlrev_b32_e32 v150, 12, v150
	v_mov_b32_e32 v151, 0
	v_lshl_add_u64 v[150:151], v[96:97], 0, v[150:151]
	global_load_dwordx4 v[86:89], v[150:151], off offset:16
	global_load_dwordx4 v[10:13], v[150:151], off
	s_mov_b64 exec, s[16:17]
	v_add_u32_e32 v0, 32, v121
	v_mul_u32_u24_e32 v99, 0xb22, v0
	v_lshrrev_b32_e32 v99, 16, v99
	v_mul_u32_u24_e32 v100, 23, v99
	v_sub_u32_e32 v100, v0, v100
	v_cmp_lt_i32_e32 vcc, 14, v100
	s_and_b64 s[92:93], s[16:17], vcc
	s_mov_b64 exec, s[92:93]
	v_mul_u32_u24_e32 v101, 15, v99
	v_sub_u32_e32 v101, v0, v101
	v_add_u32_e32 v101, s7, v101
	v_add_u32_e32 v101, -15, v101
	v_mad_i64_i32 v[150:151], vcc, v101, s25, v[94:95]
	global_load_dwordx4 v[152:155], v[150:151], off
	s_andn2_b64 exec, s[16:17], s[92:93]
	v_add_u32_e32 v101, s14, v99
	v_mul_u32_u24_e32 v101, 15, v101
	v_add_u32_e32 v150, v101, v100
	v_lshlrev_b32_e32 v150, 12, v150
	v_mov_b32_e32 v151, 0
	v_lshl_add_u64 v[150:151], v[96:97], 0, v[150:151]
	global_load_dwordx4 v[152:155], v[150:151], off offset:16
	global_load_dwordx4 v[90:93], v[150:151], off
	s_mov_b64 exec, s[16:17]
	v_add_u32_e32 v0, 48, v121
	v_mul_u32_u24_e32 v99, 0xb22, v0
	v_lshrrev_b32_e32 v99, 16, v99
	v_mul_u32_u24_e32 v100, 23, v99
	v_sub_u32_e32 v100, v0, v100
	v_cmp_lt_i32_e32 vcc, 14, v100
	s_and_b64 s[98:99], s[16:17], vcc
	s_mov_b64 exec, s[98:99]
	v_mul_u32_u24_e32 v101, 15, v99
	v_sub_u32_e32 v101, v0, v101
	v_add_u32_e32 v101, s7, v101
	v_add_u32_e32 v101, -15, v101
	v_mad_i64_i32 v[150:151], vcc, v101, s25, v[94:95]
	global_load_dwordx4 v[252:255], v[150:151], off
	s_andn2_b64 exec, s[16:17], s[98:99]
	v_add_u32_e32 v101, s14, v99
	v_mul_u32_u24_e32 v101, 15, v101
	v_add_u32_e32 v150, v101, v100
	v_lshlrev_b32_e32 v150, 12, v150
	v_mov_b32_e32 v151, 0
	v_lshl_add_u64 v[150:151], v[96:97], 0, v[150:151]
	global_load_dwordx4 v[252:255], v[150:151], off offset:16
	global_load_dwordx4 v[156:159], v[150:151], off
	s_mov_b64 exec, s[16:17]
	s_mov_b64 exec, s[20:21]
	s_waitcnt vmcnt(9)
; #define LAS __attribute__((address_space(3)))
; #define BF8_TO_F32(vw, lo, hi) const f32x4 lo = {bflo(vw.x), bfhi(vw.x), bflo(vw.y), bfhi(vw.y)}, hi = {bflo(vw.z), bfhi(vw.z), bflo(vw.w), bfhi(vw.w)}
; __device__ __forceinline__ void mix_phase(LAS unsigned char* lds, const Params& p, const int layer) {
;     ...
;                 const float* spool = p.in[2] + (size_t)layer * 128 * 15 * PW; const int bs0 = (r0 - NP) >> 3;
; #pragma unroll 2
;                 for (int i = tid >> 5; i < 92; i += 16) { const int sq = i / 23, ii = i - sq * 23; f32x4 a0, a1;
;                     if (ii < 15) { const float* sp = spool + ((size_t)(bs0 + sq) * 15 + ii) * PW + col; a0 = *(const f32x4*)sp; a1 = *(const f32x4*)(sp + 4); }
;                     else { const v4u vv = *(const v4u*)(PROJ + (size_t)(NP + (bs0 + sq) * 8 + (ii - 15)) * NC + C_UA + col); BF8_TO_F32(vv, c0_, c1_); a0 = c0_; a1 = c1_; }
;                     *(LAS f32x4*)(SL + i * 264 + q * 8) = a0; *(LAS f32x4*)(SL + i * 264 + q * 8 + 4) = a1; }
	v_lshlrev_b32_e32 v2, 16, v6
	v_and_b32_e32 v3, 0xffff0000, v6
	v_lshlrev_b32_e32 v4, 16, v7
	v_and_b32_e32 v5, 0xffff0000, v7
	v_lshlrev_b32_e32 v6, 16, v8
	v_and_b32_e32 v7, 0xffff0000, v8
	v_lshlrev_b32_e32 v8, 16, v9
	v_and_b32_e32 v9, 0xffff0000, v9
	s_mov_b64 exec, s[16:17]
	ds_write_b128 v98, v[2:5]
	ds_write_b128 v98, v[6:9] offset:16
	s_mov_b64 exec, s[90:91]
	s_waitcnt vmcnt(6)
	v_lshlrev_b32_e32 v10, 16, v86
	v_and_b32_e32 v11, 0xffff0000, v86
	v_lshlrev_b32_e32 v12, 16, v87
	v_and_b32_e32 v13, 0xffff0000, v87
	v_lshlrev_b32_e32 v86, 16, v88
	v_and_b32_e32 v87, 0xffff0000, v88
	v_lshlrev_b32_e32 v88, 16, v89
	v_and_b32_e32 v89, 0xffff0000, v89
	s_mov_b64 exec, s[16:17]
	ds_write_b128 v98, v[10:13] offset:16896
	ds_write_b128 v98, v[86:89] offset:16912
	s_mov_b64 exec, s[92:93]
	s_waitcnt vmcnt(3)
	v_lshlrev_b32_e32 v90, 16, v152
	v_and_b32_e32 v91, 0xffff0000, v152
	v_lshlrev_b32_e32 v92, 16, v153
	v_and_b32_e32 v93, 0xffff0000, v153
	v_lshlrev_b32_e32 v152, 16, v154
	v_and_b32_e32 v153, 0xffff0000, v154
	v_lshlrev_b32_e32 v154, 16, v155
	v_and_b32_e32 v155, 0xffff0000, v155
	s_mov_b64 exec, s[16:17]
	ds_write_b128 v98, v[90:93] offset:33792
	ds_write_b128 v98, v[152:155] offset:33808
	s_mov_b64 exec, s[98:99]
	s_waitcnt vmcnt(0)
	v_lshlrev_b32_e32 v156, 16, v252
	v_and_b32_e32 v157, 0xffff0000, v252
	v_lshlrev_b32_e32 v158, 16, v253
	v_and_b32_e32 v159, 0xffff0000, v253
	v_lshlrev_b32_e32 v252, 16, v254
	v_and_b32_e32 v253, 0xffff0000, v254
	v_lshlrev_b32_e32 v254, 16, v255
	v_and_b32_e32 v255, 0xffff0000, v255
	s_mov_b64 exec, s[16:17]
	ds_write_b128 v98, v[156:159] offset:50688
	ds_write_b128 v98, v[252:255] offset:50704
	v_add_u32_e32 v0, 64, v121
	v_mul_u32_u24_e32 v99, 0xb22, v0
	v_lshrrev_b32_e32 v99, 16, v99
	v_mul_u32_u24_e32 v100, 23, v99
	v_sub_u32_e32 v100, v0, v100
	v_cmp_lt_i32_e32 vcc, 14, v100
	s_and_b64 s[20:21], s[16:17], vcc
	s_mov_b64 exec, s[20:21]
	v_mul_u32_u24_e32 v101, 15, v99
	v_sub_u32_e32 v101, v0, v101
	v_add_u32_e32 v101, s7, v101
	v_add_u32_e32 v101, -15, v101
	v_mad_i64_i32 v[150:151], vcc, v101, s25, v[94:95]
	global_load_dwordx4 v[6:9], v[150:151], off
	s_andn2_b64 exec, s[16:17], s[20:21]
	v_add_u32_e32 v101, s14, v99
	v_mul_u32_u24_e32 v101, 15, v101
	v_add_u32_e32 v150, v101, v100
	v_lshlrev_b32_e32 v150, 12, v150
	v_mov_b32_e32 v151, 0
	v_lshl_add_u64 v[150:151], v[96:97], 0, v[150:151]
	global_load_dwordx4 v[6:9], v[150:151], off offset:16
	global_load_dwordx4 v[2:5], v[150:151], off
	s_mov_b64 exec, s[16:17]
	v_cmp_gt_i32_e32 vcc, 12, v121
	s_and_b64 s[100:101], s[16:17], vcc
	v_add_u32_e32 v0, 80, v121
	v_mul_u32_u24_e32 v99, 0xb22, v0
	v_lshrrev_b32_e32 v99, 16, v99
	v_mul_u32_u24_e32 v100, 23, v99
	v_sub_u32_e32 v100, v0, v100
	v_cmp_lt_i32_e32 vcc, 14, v100
	s_and_b64 s[90:91], s[100:101], vcc
	s_mov_b64 exec, s[90:91]
	v_mul_u32_u24_e32 v101, 15, v99
	v_sub_u32_e32 v101, v0, v101
	v_add_u32_e32 v101, s7, v101
	v_add_u32_e32 v101, -15, v101
	v_mad_i64_i32 v[150:151], vcc, v101, s25, v[94:95]
	global_load_dwordx4 v[86:89], v[150:151], off
	s_andn2_b64 exec, s[100:101], s[90:91]
	v_add_u32_e32 v101, s14, v99
	v_mul_u32_u24_e32 v101, 15, v101
	v_add_u32_e32 v150, v101, v100
	v_lshlrev_b32_e32 v150, 12, v150
	v_mov_b32_e32 v151, 0
	v_lshl_add_u64 v[150:151], v[96:97], 0, v[150:151]
	global_load_dwordx4 v[86:89], v[150:151], off offset:16
	global_load_dwordx4 v[10:13], v[150:151], off
	s_mov_b64 exec, s[100:101]
	s_mov_b64 exec, s[16:17]
	s_mov_b64 exec, s[20:21]
	s_waitcnt vmcnt(3)
	v_lshlrev_b32_e32 v2, 16, v6
	v_and_b32_e32 v3, 0xffff0000, v6
	v_lshlrev_b32_e32 v4, 16, v7
	v_and_b32_e32 v5, 0xffff0000, v7
	v_lshlrev_b32_e32 v6, 16, v8
	v_and_b32_e32 v7, 0xffff0000, v8
	v_lshlrev_b32_e32 v8, 16, v9
	v_and_b32_e32 v9, 0xffff0000, v9
	s_mov_b64 exec, s[16:17]
	ds_write_b128 v161, v[2:5]
	ds_write_b128 v161, v[6:9] offset:16
	s_mov_b64 exec, s[90:91]
	s_waitcnt vmcnt(0)
	v_lshlrev_b32_e32 v10, 16, v86
	v_and_b32_e32 v11, 0xffff0000, v86
	v_lshlrev_b32_e32 v12, 16, v87
	v_and_b32_e32 v13, 0xffff0000, v87
	v_lshlrev_b32_e32 v86, 16, v88
	v_and_b32_e32 v87, 0xffff0000, v88
	v_lshlrev_b32_e32 v88, 16, v89
	v_and_b32_e32 v89, 0xffff0000, v89
	s_mov_b64 exec, s[100:101]
	ds_write_b128 v161, v[10:13] offset:16896
	ds_write_b128 v161, v[86:89] offset:16912
	s_mov_b64 exec, s[16:17]

; __device__ __forceinline__ void ln_phase(const Params& p, const int layer, const int row_lo, const int row_hi, const int wg_id, const int n_wg) {
;     int tid_ = threadIdx.x; asm volatile("" : "+v"(tid_)); const int tid = tid_, lane = tid & 63, wave = tid >> 6;
;     const int gw = wg_id * NWAVES + wave, NGW = n_wg * NWAVES;
;     unsigned char* ws = p.ws; asm volatile("" : "+s"(ws)); float* Z = p.out; bf16* XB = (bf16*)(ws + WS_XB);
;     const float* g = p.in[19] + layer * DM; const float* bb = p.in[20] + layer * DM;
;     const bf16* OB = (const bf16*)(ws + WS_TMP);
;     for (int m0 = row_lo + gw; m0 < row_hi; m0 += 2 * NGW) {
;         const int m1r = m0 + NGW; const bool ok1 = m1r < row_hi; const int m1 = ok1 ? m1r : m0;
;         const v2u* ob0 = (const v2u*)(OB + (size_t)m0 * DM) + lane; const v2u* ob1 = (const v2u*)(OB + (size_t)m1 * DM) + lane;
;         f32x4 v0[8], v1[8]; v2u w0[8], w1[8]; float s0 = 0.f, s1 = 0.f;
;     ...
;         for (int j = 0; j < 8; ++j) { const f32x4 gv = *((const f32x4*)g + lane + 64 * j), bv = *((const f32x4*)bb + lane + 64 * j);
.LBB0_787:
	v_readlane_b32 s2, v249, 34
	v_readlane_b32 s3, v249, 35
	s_and_b64 s[0:1], s[0:1], s[2:3]
	s_andn2_b64 vcc, exec, s[0:1]
	s_cbranch_vccnz .LBB0_860
	v_mov_b32_e32 v0, v193
	v_readlane_b32 s68, v251, 1
	s_waitcnt vmcnt(1)
	v_ashrrev_i32_e32 v2, 6, v0
	v_readlane_b32 s2, v249, 38
	v_readlane_b32 s72, v251, 5
	v_readlane_b32 s73, v251, 6
	v_add_u32_e32 v66, s2, v2
	s_movk_i32 s2, 0x1800
	s_mov_b64 s[0:1], s[72:73]
	v_cmp_gt_i32_e32 vcc, s2, v66
	v_readlane_b32 s69, v251, 2
	v_readlane_b32 s70, v251, 3
	v_readlane_b32 s71, v251, 4
	v_readlane_b32 s74, v251, 7
	v_readlane_b32 s75, v251, 8
	s_and_saveexec_b64 s[6:7], vcc
	s_cbranch_execz .LBB0_859
	s_add_u32 s2, s0, 0x21b04000
	v_and_b32_e32 v0, 63, v0
	s_addc_u32 s3, s1, 0
	v_lshlrev_b32_e32 v2, 3, v0
	v_mov_b32_e32 v3, v1
	v_lshl_add_u64 v[68:69], s[2:3], 0, v[2:3]
	v_lshl_add_u64 v[4:5], s[0:1], 0, v[2:3]
	s_mov_b64 s[0:1], 0x7b04000
	v_and_b32_e32 v3, 64, v223
	v_lshl_add_u64 v[70:71], v[4:5], 0, s[0:1]
	v_add_u32_e32 v3, 64, v3
	v_xor_b32_e32 v4, 1, v223
	v_cmp_lt_i32_e32 vcc, v4, v3
	v_readlane_b32 s0, v248, 40
	v_lshlrev_b32_e32 v0, 4, v0
	v_cndmask_b32_e32 v4, v223, v4, vcc
	v_lshlrev_b32_e32 v142, 2, v4
	v_xor_b32_e32 v4, 2, v223
	v_cmp_lt_i32_e32 vcc, v4, v3
	v_readlane_b32 s1, v248, 41
	v_ashrrev_i32_e32 v67, 31, v66
	v_cndmask_b32_e32 v4, v223, v4, vcc
	v_lshlrev_b32_e32 v143, 2, v4
	v_xor_b32_e32 v4, 4, v223
	v_cmp_lt_i32_e32 vcc, v4, v3
	v_lshl_add_u64 v[74:75], s[0:1], 0, v[0:1]
	v_readlane_b32 s0, v248, 38
	v_cndmask_b32_e32 v4, v223, v4, vcc
	v_lshlrev_b32_e32 v144, 2, v4
	v_xor_b32_e32 v4, 8, v223
	v_cmp_lt_i32_e32 vcc, v4, v3
	v_readlane_b32 s1, v248, 39
	v_readlane_b32 s68, v251, 1
	v_cndmask_b32_e32 v4, v223, v4, vcc
	v_lshlrev_b32_e32 v145, 2, v4
	v_xor_b32_e32 v4, 16, v223
	v_lshl_add_u64 v[76:77], s[0:1], 0, v[0:1]
	s_mov_b64 s[0:1], 0x1000
	v_cmp_lt_i32_e32 vcc, v4, v3
	v_lshl_add_u64 v[78:79], v[74:75], 0, s[0:1]
	v_lshl_add_u64 v[80:81], v[76:77], 0, s[0:1]
	s_mov_b64 s[0:1], 0x1400
	v_cndmask_b32_e32 v4, v223, v4, vcc
	v_lshl_add_u64 v[82:83], v[74:75], 0, s[0:1]
	v_lshl_add_u64 v[84:85], v[76:77], 0, s[0:1]
	s_mov_b64 s[0:1], 0x1800
	v_lshlrev_b32_e32 v146, 2, v4
	v_xor_b32_e32 v4, 32, v223
	v_lshl_add_u64 v[86:87], v[74:75], 0, s[0:1]
	v_lshl_add_u64 v[88:89], v[76:77], 0, s[0:1]
	s_mov_b64 s[0:1], 0x1c00
	v_cmp_lt_i32_e32 vcc, v4, v3
	v_lshl_add_u64 v[90:91], v[74:75], 0, s[0:1]
	v_lshl_add_u64 v[92:93], v[76:77], 0, s[0:1]
	s_mov_b64 s[0:1], s[46:47]
	s_mov_b32 s5, s50
	s_mov_b32 s13, s51
	v_readlane_b32 s36, v251, 21
	v_lshlrev_b64 v[6:7], 12, v[66:67]
	v_cndmask_b32_e32 v3, v223, v4, vcc
	v_readlane_b32 s70, v251, 3
	v_readlane_b32 s71, v251, 4
	v_readlane_b32 s37, v251, 22
	v_readlane_b32 s46, v251, 31
	v_readlane_b32 s47, v251, 32
	v_readlane_b32 s50, v251, 35
	v_readlane_b32 s51, v251, 36
	v_lshlrev_b64 v[4:5], 13, v[66:67]
	v_or_b32_e32 v6, v6, v2
	v_lshlrev_b32_e32 v147, 2, v3
	v_lshl_add_u64 v[72:73], s[70:71], 0, v[0:1]
	s_mov_b32 s51, s13
	s_mov_b32 s50, s5
	s_mov_b64 s[46:47], s[0:1]
	v_lshl_add_u64 v[94:95], s[36:37], 0, v[0:1]
	v_lshl_add_u64 v[96:97], s[36:37], 0, v[4:5]
	v_lshl_add_u64 v[98:99], s[2:3], 0, v[6:7]
	v_lshl_add_u64 v[100:101], s[70:71], 0, v[4:5]
	s_mov_b64 s[52:53], 0
	v_readlane_b32 s69, v251, 2
	v_readlane_b32 s72, v251, 5
	v_readlane_b32 s73, v251, 6
	v_readlane_b32 s74, v251, 7
	v_readlane_b32 s75, v251, 8
	v_readlane_b32 s38, v251, 23
	v_readlane_b32 s39, v251, 24
	v_readlane_b32 s40, v251, 25
	v_readlane_b32 s41, v251, 26
	v_readlane_b32 s42, v251, 27
	v_readlane_b32 s43, v251, 28
	v_readlane_b32 s44, v251, 29
	v_readlane_b32 s45, v251, 30
	v_readlane_b32 s48, v251, 33
	v_readlane_b32 s49, v251, 34
	global_load_dwordx4 v[152:155], v[74:75], off
	global_load_dwordx4 v[156:159], v[74:75], off offset:1024
	global_load_dwordx4 v[160:163], v[74:75], off offset:2048
	global_load_dwordx4 v[180:183], v[74:75], off offset:3072
	global_load_dwordx4 v[228:231], v[78:79], off
	global_load_dwordx4 v[232:235], v[82:83], off
	global_load_dwordx4 v[236:239], v[86:87], off
	global_load_dwordx4 v[244:247], v[90:91], off
	global_load_dwordx4 v[184:187], v[76:77], off
	global_load_dwordx4 v[196:199], v[76:77], off offset:1024
	global_load_dwordx4 v[210:213], v[76:77], off offset:2048
	global_load_dwordx4 v[224:227], v[76:77], off offset:3072
	global_load_dwordx4 v[78:81], v[80:81], off
	global_load_dwordx4 v[82:85], v[84:85], off
	global_load_dwordx4 v[86:89], v[88:89], off
	global_load_dwordx4 v[90:93], v[92:93], off
	s_branch .LBB0_792

; __device__ __forceinline__ float bflo(unsigned w) { return __uint_as_float(w << 16); }
; __device__ __forceinline__ float bfhi(unsigned w) { return __uint_as_float(w & 0xffff0000u); }
; __device__ __forceinline__ void ln_phase(const Params& p, const int layer, const int row_lo, const int row_hi, const int wg_id, const int n_wg) {
;     ...
;         const v2u* ob0 = (const v2u*)(OB + (size_t)m0 * DM) + lane; const v2u* ob1 = (const v2u*)(OB + (size_t)m1 * DM) + lane;
;         f32x4 v0[8], v1[8]; v2u w0[8], w1[8]; float s0 = 0.f, s1 = 0.f;
;         if (layer == 0) {
;             const f32x4* xr0 = (const f32x4*)((m0 < NP) ? p.in[0] + (size_t)m0 * DM : p.in[1] + (size_t)(m0 - NP) * DM) + lane;
;             const f32x4* xr1 = (const f32x4*)((m1 < NP) ? p.in[0] + (size_t)m1 * DM : p.in[1] + (size_t)(m1 - NP) * DM) + lane;
; #pragma unroll
;             for (int j = 0; j < 8; ++j) { v0[j] = xr0[64 * j]; v1[j] = xr1[64 * j]; w0[j] = ob0[64 * j]; w1[j] = ob1[64 * j]; }
;         } else {
;             const v2u* xb0 = (const v2u*)(XB + (size_t)m0 * DM) + lane; const v2u* xb1 = (const v2u*)(XB + (size_t)m1 * DM) + lane;
;             v2u a0[8], a1[8];
; #pragma unroll
;             for (int j = 0; j < 8; ++j) { a0[j] = xb0[64 * j]; a1[j] = xb1[64 * j]; w0[j] = ob0[64 * j]; w1[j] = ob1[64 * j]; }
; #pragma unroll
;             for (int j = 0; j < 8; ++j) { v0[j] = (f32x4){bflo(a0[j].x), bfhi(a0[j].x), bflo(a0[j].y), bfhi(a0[j].y)}; v1[j] = (f32x4){bflo(a1[j].x), bfhi(a1[j].x), bflo(a1[j].y), bfhi(a1[j].y)}; }
;         }
; #pragma unroll
;         for (int j = 0; j < 8; ++j) { v0[j] = v0[j] * DN_ALPHA + (f32x4){bflo(w0[j].x), bfhi(w0[j].x), bflo(w0[j].y), bfhi(w0[j].y)};
;             v1[j] = v1[j] * DN_ALPHA + (f32x4){bflo(w1[j].x), bfhi(w1[j].x), bflo(w1[j].y), bfhi(w1[j].y)};
;             s0 += (v0[j].x + v0[j].y) + (v0[j].z + v0[j].w); s1 += (v1[j].x + v1[j].y) + (v1[j].z + v1[j].w); }
.LBB0_796:
	v_lshlrev_b64 v[102:103], 1, v[104:105]
	v_lshl_add_u64 v[110:111], v[68:69], 0, v[102:103]
	global_load_dwordx2 v[118:119], v[98:99], off offset:3584
	global_load_dwordx2 v[120:121], v[98:99], off offset:3072
	global_load_dwordx2 v[122:123], v[98:99], off offset:2560
	global_load_dwordx2 v[126:127], v[98:99], off offset:2048
	global_load_dwordx2 v[130:131], v[98:99], off offset:1536
	global_load_dwordx2 v[106:107], v[98:99], off offset:1024
	global_load_dwordx2 v[138:139], v[98:99], off offset:512
	global_load_dwordx2 v[112:113], v[98:99], off
	global_load_dwordx2 v[140:141], v[110:111], off
	global_load_dwordx2 v[148:149], v[110:111], off offset:512
	global_load_dwordx2 v[108:109], v[110:111], off offset:1024
	global_load_dwordx2 v[136:137], v[110:111], off offset:1536
	global_load_dwordx2 v[134:135], v[110:111], off offset:2048
	global_load_dwordx2 v[132:133], v[110:111], off offset:2560
	global_load_dwordx2 v[128:129], v[110:111], off offset:3072
	global_load_dwordx2 v[124:125], v[110:111], off offset:3584
	v_lshl_add_u64 v[104:105], v[104:105], 2, v[72:73]
	s_waitcnt lgkmcnt(0)
	s_waitcnt vmcnt(8)
	v_lshlrev_b32_e32 v110, 16, v112
	v_and_b32_e32 v111, 0xffff0000, v112
	v_lshlrev_b32_e32 v112, 16, v113
	v_and_b32_e32 v113, 0xffff0000, v113
	v_pk_fma_f32 v[114:115], v[64:65], s[4:5], v[112:113] op_sel_hi:[1,0,1]
	v_pk_fma_f32 v[116:117], v[62:63], s[4:5], v[110:111] op_sel_hi:[1,0,1]
	s_waitcnt vmcnt(7)
	v_lshlrev_b32_e32 v62, 16, v140
	v_and_b32_e32 v63, 0xffff0000, v140
	v_lshlrev_b32_e32 v64, 16, v141
	v_and_b32_e32 v65, 0xffff0000, v141
	v_pk_fma_f32 v[110:111], v[60:61], s[4:5], v[64:65] op_sel_hi:[1,0,1]
	v_pk_fma_f32 v[112:113], v[58:59], s[4:5], v[62:63] op_sel_hi:[1,0,1]
	v_lshlrev_b32_e32 v58, 16, v138
	v_and_b32_e32 v59, 0xffff0000, v138
	v_lshlrev_b32_e32 v60, 16, v139
	v_and_b32_e32 v61, 0xffff0000, v139
	v_pk_fma_f32 v[56:57], v[56:57], s[4:5], v[60:61] op_sel_hi:[1,0,1]
	v_pk_fma_f32 v[54:55], v[54:55], s[4:5], v[58:59] op_sel_hi:[1,0,1]
	s_waitcnt vmcnt(6)
	v_lshlrev_b32_e32 v58, 16, v148
	v_and_b32_e32 v59, 0xffff0000, v148
	v_lshlrev_b32_e32 v60, 16, v149
	v_and_b32_e32 v61, 0xffff0000, v149
	v_pk_fma_f32 v[52:53], v[52:53], s[4:5], v[60:61] op_sel_hi:[1,0,1]
	v_pk_fma_f32 v[50:51], v[50:51], s[4:5], v[58:59] op_sel_hi:[1,0,1]
	v_mov_b32_e32 v58, v54
	v_mov_b32_e32 v59, v116
	v_mov_b32_e32 v60, v55
	v_mov_b32_e32 v61, v117
	v_pk_add_f32 v[58:59], v[58:59], v[60:61]
	v_mov_b32_e32 v60, v57
	v_mov_b32_e32 v61, v115
	v_mov_b32_e32 v62, v56
	v_mov_b32_e32 v63, v114
	v_pk_add_f32 v[60:61], v[60:61], v[62:63]
	v_mov_b32_e32 v62, v111
	v_pk_add_f32 v[58:59], v[58:59], v[60:61]
	v_mov_b32_e32 v60, v113
	v_add_f32_e32 v59, 0, v59
	v_add_f32_e32 v139, v58, v59
	v_mov_b32_e32 v58, v112
	v_mov_b32_e32 v59, v50
	v_mov_b32_e32 v61, v51
	v_pk_add_f32 v[58:59], v[58:59], v[60:61]
	v_mov_b32_e32 v60, v110
	v_mov_b32_e32 v61, v52
	v_mov_b32_e32 v63, v53
	v_pk_add_f32 v[60:61], v[60:61], v[62:63]
	s_nop 0
	v_pk_add_f32 v[58:59], v[58:59], v[60:61]
	v_lshlrev_b32_e32 v60, 16, v107
	v_add_f32_e32 v58, 0, v58
	v_add_f32_e32 v140, v58, v59
	v_lshlrev_b32_e32 v58, 16, v106
	v_and_b32_e32 v59, 0xffff0000, v106
	v_and_b32_e32 v61, 0xffff0000, v107
	v_pk_fma_f32 v[46:47], v[46:47], s[4:5], v[58:59] op_sel_hi:[1,0,1]
	v_pk_fma_f32 v[48:49], v[48:49], s[4:5], v[60:61] op_sel_hi:[1,0,1]
	s_waitcnt vmcnt(5)
	v_lshlrev_b32_e32 v58, 16, v108
	v_and_b32_e32 v59, 0xffff0000, v108
	v_lshlrev_b32_e32 v60, 16, v109
	v_and_b32_e32 v61, 0xffff0000, v109
	v_pk_fma_f32 v[108:109], v[44:45], s[4:5], v[60:61] op_sel_hi:[1,0,1]
	v_pk_fma_f32 v[106:107], v[42:43], s[4:5], v[58:59] op_sel_hi:[1,0,1]
	v_mov_b32_e32 v42, v46
	v_mov_b32_e32 v43, v49
	v_pk_mov_b32 v[44:45], v[46:47], v[48:49] op_sel:[1,0]
	s_nop 0
	v_pk_add_f32 v[42:43], v[42:43], v[44:45]
	v_mov_b32_e32 v44, v106
	v_pk_add_f32 v[148:149], v[42:43], v[42:43] op_sel_hi:[0,1]
	v_pk_mov_b32 v[42:43], v[106:107], v[108:109] op_sel:[1,0]
	v_mov_b32_e32 v45, v109
	v_pk_add_f32 v[42:43], v[42:43], v[44:45]
	v_lshlrev_b32_e32 v44, 16, v131
	v_pk_add_f32 v[150:151], v[42:43], v[42:43] op_sel:[0,1] op_sel_hi:[1,0]
	v_lshlrev_b32_e32 v42, 16, v130
	v_and_b32_e32 v43, 0xffff0000, v130
	v_and_b32_e32 v45, 0xffff0000, v131
	v_pk_fma_f32 v[64:65], v[28:29], s[4:5], v[44:45] op_sel_hi:[1,0,1]
	v_pk_fma_f32 v[62:63], v[26:27], s[4:5], v[42:43] op_sel_hi:[1,0,1]
	v_lshlrev_b32_e32 v42, 16, v126
	v_and_b32_e32 v43, 0xffff0000, v126
	v_lshlrev_b32_e32 v44, 16, v127
	v_and_b32_e32 v45, 0xffff0000, v127
	s_waitcnt vmcnt(4)
	v_lshlrev_b32_e32 v26, 16, v136
	v_and_b32_e32 v27, 0xffff0000, v136
	v_lshlrev_b32_e32 v28, 16, v137
	v_and_b32_e32 v29, 0xffff0000, v137
	v_pk_fma_f32 v[44:45], v[36:37], s[4:5], v[44:45] op_sel_hi:[1,0,1]
	v_pk_fma_f32 v[42:43], v[34:35], s[4:5], v[42:43] op_sel_hi:[1,0,1]
	v_pk_fma_f32 v[60:61], v[24:25], s[4:5], v[28:29] op_sel_hi:[1,0,1]
	v_pk_fma_f32 v[58:59], v[22:23], s[4:5], v[26:27] op_sel_hi:[1,0,1]
	v_add_f32_e32 v23, v62, v63
	v_add_f32_e32 v25, v65, v64
	s_waitcnt vmcnt(3)
; __device__ __forceinline__ float bflo(unsigned w) { return __uint_as_float(w << 16); }
; __device__ __forceinline__ float bfhi(unsigned w) { return __uint_as_float(w & 0xffff0000u); }
; __device__ __forceinline__ void ln_phase(const Params& p, const int layer, const int row_lo, const int row_hi, const int wg_id, const int n_wg) {
;     ...
;         for (int j = 0; j < 8; ++j) { v0[j] = v0[j] * DN_ALPHA + (f32x4){bflo(w0[j].x), bfhi(w0[j].x), bflo(w0[j].y), bfhi(w0[j].y)};
;             v1[j] = v1[j] * DN_ALPHA + (f32x4){bflo(w1[j].x), bfhi(w1[j].x), bflo(w1[j].y), bfhi(w1[j].y)};
;             s0 += (v0[j].x + v0[j].y) + (v0[j].z + v0[j].w); s1 += (v1[j].x + v1[j].y) + (v1[j].z + v1[j].w); }
;         const float mean0 = wave_sum(s0) * (1.f / DM), mean1 = wave_sum(s1) * (1.f / DM); float q0 = 0.f, q1 = 0.f;
; #pragma unroll
;         for (int j = 0; j < 8; ++j) { v0[j] = v0[j] - mean0; v1[j] = v1[j] - mean1;
;             q0 += (v0[j].x * v0[j].x + v0[j].y * v0[j].y) + (v0[j].z * v0[j].z + v0[j].w * v0[j].w); q1 += (v1[j].x * v1[j].x + v1[j].y * v1[j].y) + (v1[j].z * v1[j].z + v1[j].w * v1[j].w); }
	v_lshlrev_b32_e32 v34, 16, v134
	v_and_b32_e32 v35, 0xffff0000, v134
	v_lshlrev_b32_e32 v36, 16, v135
	v_and_b32_e32 v37, 0xffff0000, v135
	v_mov_b32_e32 v22, v42
	v_mov_b32_e32 v24, v43
	v_mov_b32_e32 v148, v45
	v_mov_b32_e32 v138, v44
	v_pk_fma_f32 v[40:41], v[40:41], s[4:5], v[36:37] op_sel_hi:[1,0,1]
	v_pk_fma_f32 v[38:39], v[38:39], s[4:5], v[34:35] op_sel_hi:[1,0,1]
	v_pk_add_f32 v[22:23], v[22:23], v[24:25]
	v_pk_add_f32 v[24:25], v[148:149], v[138:139]
	v_add_f32_e32 v26, v58, v59
	v_add_f32_e32 v28, v60, v61
	v_pk_add_f32 v[22:23], v[22:23], v[24:25]
	v_mov_b32_e32 v141, v38
	v_mov_b32_e32 v151, v39
	v_mov_b32_e32 v27, v40
	v_mov_b32_e32 v29, v41
	v_pk_add_f32 v[126:127], v[22:23], v[22:23] op_sel_hi:[0,1]
	v_pk_add_f32 v[22:23], v[140:141], v[150:151]
	v_pk_add_f32 v[24:25], v[26:27], v[28:29]
	s_nop 0
	v_pk_add_f32 v[22:23], v[22:23], v[24:25]
	v_lshlrev_b32_e32 v24, 16, v123
	v_pk_add_f32 v[130:131], v[22:23], v[22:23] op_sel:[0,1] op_sel_hi:[1,0]
	v_lshlrev_b32_e32 v22, 16, v122
	v_and_b32_e32 v23, 0xffff0000, v122
	v_and_b32_e32 v25, 0xffff0000, v123
	v_pk_fma_f32 v[34:35], v[14:15], s[4:5], v[22:23] op_sel_hi:[1,0,1]
	v_pk_fma_f32 v[36:37], v[16:17], s[4:5], v[24:25] op_sel_hi:[1,0,1]
	s_waitcnt vmcnt(2)
	v_lshlrev_b32_e32 v14, 16, v132
	v_and_b32_e32 v15, 0xffff0000, v132
	v_lshlrev_b32_e32 v16, 16, v133
	v_and_b32_e32 v17, 0xffff0000, v133
	v_pk_fma_f32 v[32:33], v[32:33], s[4:5], v[16:17] op_sel_hi:[1,0,1]
	v_pk_fma_f32 v[30:31], v[30:31], s[4:5], v[14:15] op_sel_hi:[1,0,1]
	v_mov_b32_e32 v14, v34
	v_mov_b32_e32 v15, v37
	v_pk_mov_b32 v[16:17], v[34:35], v[36:37] op_sel:[1,0]
	s_nop 0
	v_pk_add_f32 v[14:15], v[14:15], v[16:17]
	v_mov_b32_e32 v16, v30
	v_pk_add_f32 v[122:123], v[14:15], v[14:15] op_sel_hi:[0,1]
	v_pk_mov_b32 v[14:15], v[30:31], v[32:33] op_sel:[1,0]
	v_mov_b32_e32 v17, v33
	v_pk_add_f32 v[14:15], v[14:15], v[16:17]
	v_lshlrev_b32_e32 v16, 16, v121
	v_pk_add_f32 v[132:133], v[14:15], v[14:15] op_sel:[0,1] op_sel_hi:[1,0]
	v_lshlrev_b32_e32 v14, 16, v120
	v_and_b32_e32 v15, 0xffff0000, v120
	v_and_b32_e32 v17, 0xffff0000, v121
	v_pk_fma_f32 v[28:29], v[8:9], s[4:5], v[16:17] op_sel_hi:[1,0,1]
	v_pk_fma_f32 v[26:27], v[6:7], s[4:5], v[14:15] op_sel_hi:[1,0,1]
	s_waitcnt vmcnt(1)
	v_lshlrev_b32_e32 v8, 16, v129
	v_and_b32_e32 v9, 0xffff0000, v129
	v_lshlrev_b32_e32 v16, 16, v118
	v_and_b32_e32 v17, 0xffff0000, v118
	v_lshlrev_b32_e32 v14, 16, v119
	v_and_b32_e32 v15, 0xffff0000, v119
	v_lshlrev_b32_e32 v6, 16, v128
	v_and_b32_e32 v7, 0xffff0000, v128
	v_pk_fma_f32 v[24:25], v[20:21], s[4:5], v[8:9] op_sel_hi:[1,0,1]
	v_pk_fma_f32 v[14:15], v[4:5], s[4:5], v[14:15] op_sel_hi:[1,0,1]
	v_pk_fma_f32 v[20:21], v[2:3], s[4:5], v[16:17] op_sel_hi:[1,0,1]
	v_pk_fma_f32 v[22:23], v[18:19], s[4:5], v[6:7] op_sel_hi:[1,0,1]
	v_add_f32_e32 v7, v26, v27
	v_add_f32_e32 v9, v29, v28
	s_waitcnt vmcnt(0)
	v_lshlrev_b32_e32 v2, 16, v124
	v_and_b32_e32 v3, 0xffff0000, v124
	v_lshlrev_b32_e32 v4, 16, v125
	v_and_b32_e32 v5, 0xffff0000, v125
	v_mov_b32_e32 v6, v20
	v_mov_b32_e32 v8, v21
	v_mov_b32_e32 v122, v15
	v_mov_b32_e32 v126, v14
	v_pk_fma_f32 v[16:17], v[12:13], s[4:5], v[4:5] op_sel_hi:[1,0,1]
	v_pk_fma_f32 v[18:19], v[10:11], s[4:5], v[2:3] op_sel_hi:[1,0,1]
	v_pk_add_f32 v[2:3], v[6:7], v[8:9]
	v_pk_add_f32 v[4:5], v[122:123], v[126:127]
	v_add_f32_e32 v120, v22, v23
	v_add_f32_e32 v128, v24, v25
	v_pk_add_f32 v[2:3], v[2:3], v[4:5]
	v_mov_b32_e32 v131, v18
	v_mov_b32_e32 v133, v19
	v_mov_b32_e32 v121, v16
	v_mov_b32_e32 v129, v17
	v_add_f32_e32 v6, v2, v3
	v_pk_add_f32 v[2:3], v[130:131], v[132:133]
	v_pk_add_f32 v[4:5], v[120:121], v[128:129]
	s_nop 0
	v_pk_add_f32 v[2:3], v[2:3], v[4:5]
	s_nop 0
	v_add_f32_e32 v2, v2, v3
	ds_bpermute_b32 v3, v142, v6
	s_waitcnt lgkmcnt(0)
	v_add_f32_e32 v3, v6, v3
	ds_bpermute_b32 v4, v143, v3
	s_waitcnt lgkmcnt(0)
	v_add_f32_e32 v3, v3, v4
	ds_bpermute_b32 v4, v144, v3
	s_waitcnt lgkmcnt(0)
	v_add_f32_e32 v3, v3, v4
	ds_bpermute_b32 v4, v145, v3
	s_waitcnt lgkmcnt(0)
	v_add_f32_e32 v3, v3, v4
	ds_bpermute_b32 v4, v146, v3
	s_waitcnt lgkmcnt(0)
	v_add_f32_e32 v3, v3, v4
	ds_bpermute_b32 v4, v147, v3
	s_waitcnt lgkmcnt(0)
	v_add_f32_e32 v67, v3, v4
	ds_bpermute_b32 v3, v142, v2
	v_fmamk_f32 v117, v67, 0xba000000, v117
	v_fmac_f32_e32 v116, 0xba000000, v67
	v_fmamk_f32 v121, v67, 0xba000000, v55
	v_fmac_f32_e32 v54, 0xba000000, v67
	s_waitcnt lgkmcnt(0)
	v_add_f32_e32 v2, v2, v3
	ds_bpermute_b32 v3, v143, v2
	v_mov_b32_e32 v120, v117
	v_fmac_f32_e32 v114, 0xba000000, v67
	v_fmac_f32_e32 v56, 0xba000000, v67
	v_pk_mul_f32 v[4:5], v[120:121], v[120:121]
	s_waitcnt lgkmcnt(0)
	v_add_f32_e32 v2, v2, v3
	ds_bpermute_b32 v3, v144, v2
	v_fmamk_f32 v115, v67, 0xba000000, v115
	v_fmamk_f32 v127, v67, 0xba000000, v57
	v_mov_b32_e32 v126, v115
	v_fmamk_f32 v49, v67, 0xba000000, v49
	s_waitcnt lgkmcnt(0)
	v_add_f32_e32 v2, v2, v3
	ds_bpermute_b32 v3, v145, v2
	v_fmac_f32_e32 v48, 0xba000000, v67
	v_fmamk_f32 v47, v67, 0xba000000, v47
	v_fmac_f32_e32 v46, 0xba000000, v67
	v_fmac_f32_e32 v62, 0xba000000, v67
	s_waitcnt lgkmcnt(0)
	v_add_f32_e32 v2, v2, v3
	ds_bpermute_b32 v3, v146, v2
	v_fmac_f32_e32 v64, 0xba000000, v67
	v_fmamk_f32 v63, v67, 0xba000000, v63
	v_fmamk_f32 v65, v67, 0xba000000, v65
	v_fmamk_f32 v45, v67, 0xba000000, v45
	s_waitcnt lgkmcnt(0)
	v_add_f32_e32 v2, v2, v3
	ds_bpermute_b32 v3, v147, v2
	v_fmac_f32_e32 v44, 0xba000000, v67
	v_fmamk_f32 v43, v67, 0xba000000, v43
	v_fmac_f32_e32 v42, 0xba000000, v67
	v_fmamk_f32 v37, v67, 0xba000000, v37
	s_waitcnt lgkmcnt(0)
; __device__ __forceinline__ void ln_phase(const Params& p, const int layer, const int row_lo, const int row_hi, const int wg_id, const int n_wg) {
;     ...
;         const float mean0 = wave_sum(s0) * (1.f / DM), mean1 = wave_sum(s1) * (1.f / DM); float q0 = 0.f, q1 = 0.f;
; #pragma unroll
;         for (int j = 0; j < 8; ++j) { v0[j] = v0[j] - mean0; v1[j] = v1[j] - mean1;
;             q0 += (v0[j].x * v0[j].x + v0[j].y * v0[j].y) + (v0[j].z * v0[j].z + v0[j].w * v0[j].w); q1 += (v1[j].x * v1[j].x + v1[j].y * v1[j].y) + (v1[j].z * v1[j].z + v1[j].w * v1[j].w); }
;         const float rstd0 = 1.f / sqrtf(wave_sum(q0) * (1.f / DM) + LN_EPS), rstd1 = 1.f / sqrtf(wave_sum(q1) * (1.f / DM) + LN_EPS);
	v_add_f32_e32 v130, v2, v3
	v_mov_b32_e32 v2, v116
	v_mov_b32_e32 v3, v54
	v_pk_fma_f32 v[2:3], v[2:3], v[2:3], v[4:5]
	v_mov_b32_e32 v4, v114
	v_mov_b32_e32 v5, v56
	v_fmamk_f32 v113, v130, 0xba000000, v113
	v_pk_mul_f32 v[4:5], v[4:5], v[4:5]
	v_fmamk_f32 v111, v130, 0xba000000, v111
	v_fmac_f32_e32 v112, 0xba000000, v130
	v_fmamk_f32 v123, v130, 0xba000000, v51
	v_fmac_f32_e32 v50, 0xba000000, v130
	v_pk_fma_f32 v[4:5], v[126:127], v[126:127], v[4:5]
	v_mov_b32_e32 v122, v113
	v_fmac_f32_e32 v110, 0xba000000, v130
	v_fmamk_f32 v125, v130, 0xba000000, v53
	v_fmac_f32_e32 v52, 0xba000000, v130
	v_pk_add_f32 v[2:3], v[2:3], v[4:5]
	v_mov_b32_e32 v4, v112
	v_mov_b32_e32 v5, v50
	v_pk_mul_f32 v[6:7], v[122:123], v[122:123]
	v_mov_b32_e32 v124, v111
	v_pk_fma_f32 v[4:5], v[4:5], v[4:5], v[6:7]
	v_mov_b32_e32 v6, v110
	v_mov_b32_e32 v7, v52
	v_pk_mul_f32 v[8:9], v[124:125], v[124:125]
	v_fmamk_f32 v109, v130, 0xba000000, v109
	v_pk_fma_f32 v[6:7], v[6:7], v[6:7], v[8:9]
	v_pk_mul_f32 v[8:9], v[46:47], v[46:47]
	v_pk_add_f32 v[4:5], v[4:5], v[6:7]
	v_pk_mul_f32 v[6:7], v[48:49], v[48:49]
	v_fmac_f32_e32 v108, 0xba000000, v130
	v_fmamk_f32 v107, v130, 0xba000000, v107
	v_fmac_f32_e32 v106, 0xba000000, v130
	v_pk_mov_b32 v[10:11], v[8:9], v[6:7] op_sel:[1,0]
	v_mov_b32_e32 v9, v7
	v_pk_add_f32 v[2:3], v[2:3], v[2:3] op_sel_hi:[0,1]
	v_pk_add_f32 v[6:7], v[8:9], v[10:11]
	v_pk_mul_f32 v[8:9], v[108:109], v[108:109]
	v_pk_mul_f32 v[10:11], v[106:107], v[106:107]
	v_mul_f32_e32 v2, v62, v62
	v_pk_mov_b32 v[12:13], v[10:11], v[8:9] op_sel:[1,0]
	v_mov_b32_e32 v11, v9
	v_pk_add_f32 v[8:9], v[12:13], v[10:11]
	v_fmac_f32_e32 v58, 0xba000000, v130
	v_pk_fma_f32 v[10:11], v[62:63], v[62:63], v[2:3] op_sel_hi:[1,1,0]
	v_mul_f32_e32 v2, v64, v64
	v_fmac_f32_e32 v60, 0xba000000, v130
	v_fmamk_f32 v59, v130, 0xba000000, v59
	v_pk_fma_f32 v[12:13], v[64:65], v[64:65], v[2:3] op_sel_hi:[1,1,0]
	v_mul_f32_e32 v2, v58, v58
	v_fmamk_f32 v61, v130, 0xba000000, v61
	v_pk_fma_f32 v[118:119], v[58:59], v[58:59], v[2:3] op_sel_hi:[1,1,0]
	v_mul_f32_e32 v2, v60, v60
	v_pk_add_f32 v[4:5], v[4:5], v[4:5] op_sel_hi:[0,1]
	v_pk_add_f32 v[6:7], v[6:7], v[6:7] op_sel_hi:[0,1]
	v_pk_add_f32 v[8:9], v[8:9], v[8:9] op_sel_hi:[0,1]
	v_pk_fma_f32 v[128:129], v[60:61], v[60:61], v[2:3] op_sel_hi:[1,1,0]
	v_fmamk_f32 v41, v130, 0xba000000, v41
	v_fmac_f32_e32 v40, 0xba000000, v130
	v_fmamk_f32 v39, v130, 0xba000000, v39
	v_fmac_f32_e32 v38, 0xba000000, v130
	v_mul_f32_e32 v2, v44, v44
	v_mul_f32_e32 v6, v45, v45
	v_mul_f32_e32 v118, v38, v38
	v_mul_f32_e32 v128, v39, v39
	v_mul_f32_e32 v8, v40, v40
	v_mul_f32_e32 v4, v41, v41
	v_mul_f32_e32 v10, v42, v42
	v_mul_f32_e32 v12, v43, v43
	v_pk_add_f32 v[2:3], v[6:7], v[2:3]
	v_pk_add_f32 v[6:7], v[118:119], v[128:129]
	v_pk_add_f32 v[4:5], v[8:9], v[4:5]
	v_fmac_f32_e32 v36, 0xba000000, v67
	v_fmamk_f32 v35, v67, 0xba000000, v35
	v_fmac_f32_e32 v34, 0xba000000, v67
	v_pk_add_f32 v[10:11], v[10:11], v[12:13]
	v_pk_add_f32 v[4:5], v[6:7], v[4:5]
	v_pk_mul_f32 v[6:7], v[36:37], v[36:37]
	v_pk_mul_f32 v[8:9], v[34:35], v[34:35]
	v_pk_add_f32 v[2:3], v[10:11], v[2:3]
	v_fmamk_f32 v33, v130, 0xba000000, v33
	v_fmac_f32_e32 v32, 0xba000000, v130
	v_fmamk_f32 v31, v130, 0xba000000, v31
	v_fmac_f32_e32 v30, 0xba000000, v130
	v_pk_mov_b32 v[10:11], v[8:9], v[6:7] op_sel:[1,0]
	v_mov_b32_e32 v9, v7
	v_pk_add_f32 v[2:3], v[2:3], v[2:3] op_sel_hi:[0,1]
	v_pk_add_f32 v[6:7], v[8:9], v[10:11]
	v_pk_mul_f32 v[8:9], v[32:33], v[32:33]
	v_pk_mul_f32 v[10:11], v[30:31], v[30:31]
	v_fmac_f32_e32 v26, 0xba000000, v67
	v_pk_mov_b32 v[12:13], v[10:11], v[8:9] op_sel:[1,0]
	v_mov_b32_e32 v11, v9
	v_fmac_f32_e32 v28, 0xba000000, v67
	v_fmamk_f32 v27, v67, 0xba000000, v27
	v_mul_f32_e32 v2, v26, v26
	v_pk_add_f32 v[8:9], v[12:13], v[10:11]
	v_fmamk_f32 v29, v67, 0xba000000, v29
	v_fmac_f32_e32 v22, 0xba000000, v130
	v_pk_fma_f32 v[10:11], v[26:27], v[26:27], v[2:3] op_sel_hi:[1,1,0]
	v_mul_f32_e32 v2, v28, v28
	v_fmac_f32_e32 v24, 0xba000000, v130
	v_fmamk_f32 v23, v130, 0xba000000, v23
	v_pk_fma_f32 v[12:13], v[28:29], v[28:29], v[2:3] op_sel_hi:[1,1,0]
	v_mul_f32_e32 v2, v22, v22
	v_pk_add_f32 v[6:7], v[6:7], v[6:7] op_sel_hi:[0,1]
	v_fmamk_f32 v25, v130, 0xba000000, v25
	v_pk_fma_f32 v[118:119], v[22:23], v[22:23], v[2:3] op_sel_hi:[1,1,0]
	v_mul_f32_e32 v2, v24, v24
	v_fmamk_f32 v15, v67, 0xba000000, v15
	v_fmac_f32_e32 v14, 0xba000000, v67
	v_fmamk_f32 v21, v67, 0xba000000, v21
	v_fmac_f32_e32 v20, 0xba000000, v67
	v_pk_fma_f32 v[128:129], v[24:25], v[24:25], v[2:3] op_sel_hi:[1,1,0]
	v_mul_f32_e32 v10, v20, v20
	v_mul_f32_e32 v12, v21, v21
	v_mul_f32_e32 v2, v14, v14
	v_mul_f32_e32 v6, v15, v15
	v_pk_add_f32 v[4:5], v[4:5], v[4:5] op_sel_hi:[0,1]
	v_pk_add_f32 v[8:9], v[8:9], v[8:9] op_sel_hi:[0,1]
	v_fmamk_f32 v17, v130, 0xba000000, v17
	v_fmac_f32_e32 v16, 0xba000000, v130
	v_fmamk_f32 v19, v130, 0xba000000, v19
	v_fmac_f32_e32 v18, 0xba000000, v130
	v_pk_add_f32 v[10:11], v[10:11], v[12:13]
	v_pk_add_f32 v[2:3], v[6:7], v[2:3]
	v_mul_f32_e32 v118, v18, v18
	v_pk_add_f32 v[2:3], v[10:11], v[2:3]
	v_mul_f32_e32 v128, v19, v19
	v_mul_f32_e32 v8, v16, v16
	v_mul_f32_e32 v4, v17, v17
	v_add_f32_e32 v6, v2, v3
	v_pk_add_f32 v[2:3], v[118:119], v[128:129]
	v_pk_add_f32 v[4:5], v[8:9], v[4:5]
	v_lshl_add_u64 v[118:119], v[100:101], 0, v[0:1]
	v_pk_add_f32 v[2:3], v[2:3], v[4:5]
	s_nop 0
	v_add_f32_e32 v2, v2, v3
	ds_bpermute_b32 v3, v142, v6
	s_waitcnt lgkmcnt(0)
; __device__ __forceinline__ unsigned pk2(float lo, float hi) { return f2bf(lo) | (f2bf(hi) << 16); }
; __device__ __forceinline__ void ln_phase(const Params& p, const int layer, const int row_lo, const int row_hi, const int wg_id, const int n_wg) {
;     ...
;         const float rstd0 = 1.f / sqrtf(wave_sum(q0) * (1.f / DM) + LN_EPS), rstd1 = 1.f / sqrtf(wave_sum(q1) * (1.f / DM) + LN_EPS);
;         f32x4* zr0 = (f32x4*)(Z + (size_t)m0 * DM) + lane; f32x4* zr1 = (f32x4*)(Z + (size_t)m1 * DM) + lane;
;         unsigned long long* o80 = (unsigned long long*)(XB + (size_t)m0 * DM) + lane; unsigned long long* o81 = (unsigned long long*)(XB + (size_t)m1 * DM) + lane;
; #pragma unroll
;         for (int j = 0; j < 8; ++j) { const f32x4 gv = *((const f32x4*)g + lane + 64 * j), bv = *((const f32x4*)bb + lane + 64 * j);
;             const f32x4 y0 = v0[j] * rstd0 * gv + bv, y1 = v1[j] * rstd1 * gv + bv;
;             if (layer == 0) { o80[64 * j] = (unsigned long long)pk2(y0.x, y0.y) | ((unsigned long long)pk2(y0.z, y0.w) << 32);
;                 if (ok1) o81[64 * j] = (unsigned long long)pk2(y1.x, y1.y) | ((unsigned long long)pk2(y1.z, y1.w) << 32); }
;             else { zr0[64 * j] = y0; if (ok1) zr1[64 * j] = y1; } }
	v_add_f32_e32 v3, v6, v3
	ds_bpermute_b32 v4, v143, v3
	s_waitcnt lgkmcnt(0)
	v_add_f32_e32 v3, v3, v4
	ds_bpermute_b32 v4, v144, v3
	s_waitcnt lgkmcnt(0)
	v_add_f32_e32 v3, v3, v4
	ds_bpermute_b32 v4, v145, v3
	s_waitcnt lgkmcnt(0)
	v_add_f32_e32 v3, v3, v4
	ds_bpermute_b32 v4, v146, v3
	s_waitcnt lgkmcnt(0)
	v_add_f32_e32 v3, v3, v4
	ds_bpermute_b32 v4, v147, v3
	s_waitcnt lgkmcnt(0)
	v_add_f32_e32 v3, v3, v4
	v_fmamk_f32 v3, v3, 0x3a000000, v218
	v_cmp_gt_f32_e32 vcc, s12, v3
	v_mul_f32_e32 v4, 0x4f800000, v3
	s_nop 0
	v_cndmask_b32_e32 v3, v3, v4, vcc
	v_sqrt_f32_e32 v4, v3
	s_nop 0
	v_add_u32_e32 v5, -1, v4
	v_fma_f32 v6, -v5, v4, v3
	v_cmp_ge_f32_e64 s[0:1], 0, v6
	v_add_u32_e32 v6, 1, v4
	s_nop 0
	v_cndmask_b32_e64 v5, v4, v5, s[0:1]
	v_fma_f32 v4, -v6, v4, v3
	v_cmp_lt_f32_e64 s[0:1], 0, v4
	s_nop 1
	v_cndmask_b32_e64 v4, v5, v6, s[0:1]
	v_mul_f32_e32 v5, 0x37800000, v4
	v_cndmask_b32_e32 v4, v4, v5, vcc
	v_cmp_class_f32_e32 vcc, v3, v219
	s_nop 1
	v_cndmask_b32_e32 v3, v4, v3, vcc
	v_div_scale_f32 v4, s[0:1], v3, v3, 1.0
	v_rcp_f32_e32 v5, v4
	s_nop 0
	v_fma_f32 v6, -v4, v5, 1.0
	v_fmac_f32_e32 v5, v6, v5
	v_div_scale_f32 v6, vcc, 1.0, v3, 1.0
	v_mul_f32_e32 v7, v6, v5
	v_fma_f32 v8, -v4, v7, v6
	v_fmac_f32_e32 v7, v8, v5
	v_fma_f32 v4, -v4, v7, v6
	v_div_fmas_f32 v4, v4, v5, v7
	v_div_fixup_f32 v120, v4, v3, 1.0
	ds_bpermute_b32 v3, v142, v2
	v_pk_mul_f32 v[10:11], v[116:117], v[120:121] op_sel_hi:[1,0]
	v_pk_mul_f32 v[12:13], v[114:115], v[120:121] op_sel_hi:[1,0]
	s_waitcnt lgkmcnt(0)
	v_add_f32_e32 v2, v2, v3
	ds_bpermute_b32 v3, v143, v2
	s_waitcnt lgkmcnt(0)
	v_add_f32_e32 v2, v2, v3
	ds_bpermute_b32 v3, v144, v2
	s_waitcnt lgkmcnt(0)
	v_add_f32_e32 v2, v2, v3
	ds_bpermute_b32 v3, v145, v2
	s_waitcnt lgkmcnt(0)
	v_add_f32_e32 v2, v2, v3
	ds_bpermute_b32 v3, v146, v2
	s_waitcnt lgkmcnt(0)
	v_add_f32_e32 v2, v2, v3
	ds_bpermute_b32 v3, v147, v2
	s_waitcnt lgkmcnt(0)
	v_add_f32_e32 v2, v2, v3
	v_fmamk_f32 v2, v2, 0x3a000000, v218
	v_cmp_gt_f32_e32 vcc, s12, v2
	v_mul_f32_e32 v3, 0x4f800000, v2
	s_nop 0
	v_cndmask_b32_e32 v2, v2, v3, vcc
	v_sqrt_f32_e32 v3, v2
	s_nop 0
	v_add_u32_e32 v4, -1, v3
	v_fma_f32 v5, -v4, v3, v2
	v_cmp_ge_f32_e64 s[0:1], 0, v5
	v_add_u32_e32 v5, 1, v3
	s_nop 0
	v_cndmask_b32_e64 v4, v3, v4, s[0:1]
	v_fma_f32 v3, -v5, v3, v2
	v_cmp_lt_f32_e64 s[0:1], 0, v3
	s_nop 1
	v_cndmask_b32_e64 v3, v4, v5, s[0:1]
	v_mul_f32_e32 v4, 0x37800000, v3
	v_cndmask_b32_e32 v3, v3, v4, vcc
	v_cmp_class_f32_e32 vcc, v2, v219
	s_nop 1
	v_cndmask_b32_e32 v2, v3, v2, vcc
	v_div_scale_f32 v3, s[0:1], v2, v2, 1.0
	v_rcp_f32_e32 v4, v3
	s_mov_b64 s[0:1], -1
	v_fma_f32 v5, -v3, v4, 1.0
	v_fmac_f32_e32 v4, v5, v4
	v_div_scale_f32 v5, vcc, 1.0, v2, 1.0
	v_mul_f32_e32 v6, v5, v4
	v_fma_f32 v7, -v3, v6, v5
	v_fmac_f32_e32 v6, v7, v4
	v_fma_f32 v3, -v3, v6, v5
	v_div_fmas_f32 v3, v3, v4, v6
	v_div_fixup_f32 v122, v3, v2, 1.0
	v_mov_b64_e32 v[2:3], v[152:153]
	v_mov_b64_e32 v[4:5], v[154:155]
	v_mov_b64_e32 v[6:7], v[184:185]
	v_mov_b64_e32 v[8:9], v[186:187]
	v_pk_mul_f32 v[112:113], v[112:113], v[122:123] op_sel_hi:[1,0]
	v_pk_mul_f32 v[110:111], v[110:111], v[122:123] op_sel_hi:[1,0]
	s_and_b64 vcc, exec, s[10:11]
	v_pk_fma_f32 v[12:13], v[4:5], v[12:13], v[8:9]
	v_pk_fma_f32 v[10:11], v[2:3], v[10:11], v[6:7]
	v_pk_fma_f32 v[4:5], v[4:5], v[110:111], v[8:9]
	v_pk_fma_f32 v[2:3], v[2:3], v[112:113], v[6:7]
	s_cbranch_vccz .LBB0_800
	global_store_dwordx4 v[118:119], v[10:13], off
	s_and_saveexec_b64 s[0:1], s[38:39]
	s_cbranch_execz .LBB0_799
	global_store_dwordx4 v[104:105], v[2:5], off

; __device__ __forceinline__ unsigned pk2(float lo, float hi) { return f2bf(lo) | (f2bf(hi) << 16); }
; __device__ __forceinline__ void ln_phase(const Params& p, const int layer, const int row_lo, const int row_hi, const int wg_id, const int n_wg) {
;     ...
;         for (int j = 0; j < 8; ++j) { const f32x4 gv = *((const f32x4*)g + lane + 64 * j), bv = *((const f32x4*)bb + lane + 64 * j);
;             const f32x4 y0 = v0[j] * rstd0 * gv + bv, y1 = v1[j] * rstd1 * gv + bv;
;             if (layer == 0) { o80[64 * j] = (unsigned long long)pk2(y0.x, y0.y) | ((unsigned long long)pk2(y0.z, y0.w) << 32);
;                 if (ok1) o81[64 * j] = (unsigned long long)pk2(y1.x, y1.y) | ((unsigned long long)pk2(y1.z, y1.w) << 32); }
;             else { zr0[64 * j] = y0; if (ok1) zr1[64 * j] = y1; } }
.LBB0_804:
	v_mov_b64_e32 v[6:7], v[156:157]
	v_mov_b64_e32 v[8:9], v[158:159]
	v_mov_b64_e32 v[10:11], v[196:197]
	v_mov_b64_e32 v[12:13], v[198:199]
	v_mov_b32_e32 v55, v121
	v_mov_b32_e32 v121, v120
	v_mov_b32_e32 v2, v120
	v_mov_b32_e32 v3, v120
	v_mov_b32_e32 v57, v127
	v_mov_b32_e32 v51, v123
	v_mov_b32_e32 v123, v122
	v_pk_mul_f32 v[2:3], v[56:57], v[2:3]
	v_pk_mul_f32 v[54:55], v[54:55], v[120:121]
	v_mov_b32_e32 v53, v125
	v_pk_mul_f32 v[50:51], v[50:51], v[122:123]
	s_mov_b64 s[0:1], -1
	s_andn2_b64 vcc, exec, s[10:11]
	v_pk_fma_f32 v[4:5], v[2:3], v[8:9], v[12:13]
	v_pk_fma_f32 v[2:3], v[54:55], v[6:7], v[10:11]
	v_mov_b32_e32 v54, v122
	v_mov_b32_e32 v55, v122
	v_pk_mul_f32 v[52:53], v[52:53], v[54:55]
	v_pk_fma_f32 v[6:7], v[50:51], v[6:7], v[10:11]
	v_cndmask_b32_e64 v10, 0, 1, s[10:11]
	v_pk_fma_f32 v[8:9], v[52:53], v[8:9], v[12:13]
	v_cmp_ne_u32_e64 s[40:41], 1, v10
	s_cbranch_vccnz .LBB0_808
	global_store_dwordx4 v[118:119], v[2:5], off offset:1024
	s_and_saveexec_b64 s[0:1], s[38:39]
	s_cbranch_execz .LBB0_807
	global_store_dwordx4 v[104:105], v[6:9], off offset:1024

; __device__ __forceinline__ unsigned pk2(float lo, float hi) { return f2bf(lo) | (f2bf(hi) << 16); }
; __device__ __forceinline__ void ln_phase(const Params& p, const int layer, const int row_lo, const int row_hi, const int wg_id, const int n_wg) {
;     ...
;         for (int j = 0; j < 8; ++j) { const f32x4 gv = *((const f32x4*)g + lane + 64 * j), bv = *((const f32x4*)bb + lane + 64 * j);
;             const f32x4 y0 = v0[j] * rstd0 * gv + bv, y1 = v1[j] * rstd1 * gv + bv;
;             if (layer == 0) { o80[64 * j] = (unsigned long long)pk2(y0.x, y0.y) | ((unsigned long long)pk2(y0.z, y0.w) << 32);
;                 if (ok1) o81[64 * j] = (unsigned long long)pk2(y1.x, y1.y) | ((unsigned long long)pk2(y1.z, y1.w) << 32); }
;             else { zr0[64 * j] = y0; if (ok1) zr1[64 * j] = y1; } }
.LBB0_812:
	v_mov_b64_e32 v[2:3], v[160:161]
	v_mov_b64_e32 v[4:5], v[162:163]
	v_mov_b64_e32 v[10:11], v[210:211]
	v_mov_b64_e32 v[12:13], v[212:213]
	v_mov_b32_e32 v6, v120
	v_mov_b32_e32 v7, v120
	v_pk_mul_f32 v[6:7], v[48:49], v[6:7]
	v_pk_mul_f32 v[46:47], v[46:47], v[120:121]
	v_pk_mul_f32 v[48:49], v[106:107], v[122:123]
	s_mov_b64 s[0:1], -1
	s_and_b64 vcc, exec, s[40:41]
	v_pk_fma_f32 v[8:9], v[6:7], v[4:5], v[12:13]
	v_pk_fma_f32 v[6:7], v[46:47], v[2:3], v[10:11]
	v_mov_b32_e32 v46, v122
	v_mov_b32_e32 v47, v122
	v_pk_mul_f32 v[46:47], v[108:109], v[46:47]
	v_pk_fma_f32 v[2:3], v[48:49], v[2:3], v[10:11]
	v_pk_fma_f32 v[4:5], v[46:47], v[4:5], v[12:13]
	s_cbranch_vccnz .LBB0_816
	global_store_dwordx4 v[118:119], v[6:9], off offset:2048
	s_and_saveexec_b64 s[0:1], s[38:39]
	s_cbranch_execz .LBB0_815
	global_store_dwordx4 v[104:105], v[2:5], off offset:2048

; __device__ __forceinline__ unsigned pk2(float lo, float hi) { return f2bf(lo) | (f2bf(hi) << 16); }
; __device__ __forceinline__ void ln_phase(const Params& p, const int layer, const int row_lo, const int row_hi, const int wg_id, const int n_wg) {
;     ...
;         for (int j = 0; j < 8; ++j) { const f32x4 gv = *((const f32x4*)g + lane + 64 * j), bv = *((const f32x4*)bb + lane + 64 * j);
;             const f32x4 y0 = v0[j] * rstd0 * gv + bv, y1 = v1[j] * rstd1 * gv + bv;
;             if (layer == 0) { o80[64 * j] = (unsigned long long)pk2(y0.x, y0.y) | ((unsigned long long)pk2(y0.z, y0.w) << 32);
;                 if (ok1) o81[64 * j] = (unsigned long long)pk2(y1.x, y1.y) | ((unsigned long long)pk2(y1.z, y1.w) << 32); }
;             else { zr0[64 * j] = y0; if (ok1) zr1[64 * j] = y1; } }
.LBB0_820:
	v_mov_b64_e32 v[2:3], v[180:181]
	v_mov_b64_e32 v[4:5], v[182:183]
	v_mov_b64_e32 v[10:11], v[224:225]
	v_mov_b64_e32 v[12:13], v[226:227]
	v_mov_b32_e32 v6, v120
	v_mov_b32_e32 v7, v120
	v_pk_mul_f32 v[6:7], v[64:65], v[6:7]
	v_pk_mul_f32 v[46:47], v[62:63], v[120:121]
	v_pk_mul_f32 v[48:49], v[58:59], v[122:123]
	s_mov_b64 s[0:1], -1
	s_and_b64 vcc, exec, s[40:41]
	v_pk_fma_f32 v[8:9], v[6:7], v[4:5], v[12:13]
	v_pk_fma_f32 v[6:7], v[46:47], v[2:3], v[10:11]
	v_mov_b32_e32 v46, v122
	v_mov_b32_e32 v47, v122
	v_pk_mul_f32 v[46:47], v[60:61], v[46:47]
	v_pk_fma_f32 v[2:3], v[48:49], v[2:3], v[10:11]
	v_pk_fma_f32 v[4:5], v[46:47], v[4:5], v[12:13]
	s_cbranch_vccnz .LBB0_824
	global_store_dwordx4 v[118:119], v[6:9], off offset:3072
	s_and_saveexec_b64 s[0:1], s[38:39]
	s_cbranch_execz .LBB0_823
	global_store_dwordx4 v[104:105], v[2:5], off offset:3072

; __device__ __forceinline__ unsigned pk2(float lo, float hi) { return f2bf(lo) | (f2bf(hi) << 16); }
; __device__ __forceinline__ void ln_phase(const Params& p, const int layer, const int row_lo, const int row_hi, const int wg_id, const int n_wg) {
;     ...
;         for (int j = 0; j < 8; ++j) { const f32x4 gv = *((const f32x4*)g + lane + 64 * j), bv = *((const f32x4*)bb + lane + 64 * j);
;             const f32x4 y0 = v0[j] * rstd0 * gv + bv, y1 = v1[j] * rstd1 * gv + bv;
;             if (layer == 0) { o80[64 * j] = (unsigned long long)pk2(y0.x, y0.y) | ((unsigned long long)pk2(y0.z, y0.w) << 32);
;                 if (ok1) o81[64 * j] = (unsigned long long)pk2(y1.x, y1.y) | ((unsigned long long)pk2(y1.z, y1.w) << 32); }
;             else { zr0[64 * j] = y0; if (ok1) zr1[64 * j] = y1; } }
.LBB0_828:
	v_mov_b64_e32 v[2:3], v[228:229]
	v_mov_b64_e32 v[4:5], v[230:231]
	v_mov_b64_e32 v[10:11], v[78:79]
	v_mov_b64_e32 v[12:13], v[80:81]
	v_mov_b32_e32 v6, v120
	v_mov_b32_e32 v7, v120
	v_pk_mul_f32 v[6:7], v[44:45], v[6:7]
	v_pk_mul_f32 v[42:43], v[42:43], v[120:121]
	v_pk_mul_f32 v[38:39], v[38:39], v[122:123]
	s_mov_b64 s[0:1], -1
	s_and_b64 vcc, exec, s[40:41]
	v_pk_fma_f32 v[8:9], v[6:7], v[4:5], v[12:13]
	v_pk_fma_f32 v[6:7], v[42:43], v[2:3], v[10:11]
	v_mov_b32_e32 v42, v122
	v_mov_b32_e32 v43, v122
	v_pk_mul_f32 v[40:41], v[40:41], v[42:43]
	v_pk_fma_f32 v[2:3], v[38:39], v[2:3], v[10:11]
	v_pk_fma_f32 v[4:5], v[40:41], v[4:5], v[12:13]
	s_cbranch_vccnz .LBB0_832
	v_add_co_u32_e32 v10, vcc, 0x1000, v118
	s_nop 1
	v_addc_co_u32_e32 v11, vcc, 0, v119, vcc
	global_store_dwordx4 v[10:11], v[6:9], off
	s_and_saveexec_b64 s[0:1], s[38:39]
	s_cbranch_execz .LBB0_831
	v_add_co_u32_e32 v10, vcc, 0x1000, v104
	s_nop 1
	v_addc_co_u32_e32 v11, vcc, 0, v105, vcc
	global_store_dwordx4 v[10:11], v[2:5], off

; __device__ __forceinline__ unsigned pk2(float lo, float hi) { return f2bf(lo) | (f2bf(hi) << 16); }
; __device__ __forceinline__ void ln_phase(const Params& p, const int layer, const int row_lo, const int row_hi, const int wg_id, const int n_wg) {
;     ...
;         for (int j = 0; j < 8; ++j) { const f32x4 gv = *((const f32x4*)g + lane + 64 * j), bv = *((const f32x4*)bb + lane + 64 * j);
;             const f32x4 y0 = v0[j] * rstd0 * gv + bv, y1 = v1[j] * rstd1 * gv + bv;
;             if (layer == 0) { o80[64 * j] = (unsigned long long)pk2(y0.x, y0.y) | ((unsigned long long)pk2(y0.z, y0.w) << 32);
;                 if (ok1) o81[64 * j] = (unsigned long long)pk2(y1.x, y1.y) | ((unsigned long long)pk2(y1.z, y1.w) << 32); }
;             else { zr0[64 * j] = y0; if (ok1) zr1[64 * j] = y1; } }
.LBB0_836:
	v_mov_b64_e32 v[2:3], v[232:233]
	v_mov_b64_e32 v[4:5], v[234:235]
	v_mov_b64_e32 v[10:11], v[82:83]
	v_mov_b64_e32 v[12:13], v[84:85]
	v_mov_b32_e32 v6, v120
	v_mov_b32_e32 v7, v120
	v_pk_mul_f32 v[6:7], v[36:37], v[6:7]
	v_pk_mul_f32 v[34:35], v[34:35], v[120:121]
	v_pk_mul_f32 v[30:31], v[30:31], v[122:123]
	s_mov_b64 s[0:1], -1
	s_and_b64 vcc, exec, s[40:41]
	v_pk_fma_f32 v[8:9], v[6:7], v[4:5], v[12:13]
	v_pk_fma_f32 v[6:7], v[34:35], v[2:3], v[10:11]
	v_mov_b32_e32 v34, v122
	v_mov_b32_e32 v35, v122
	v_pk_mul_f32 v[32:33], v[32:33], v[34:35]
	v_pk_fma_f32 v[2:3], v[30:31], v[2:3], v[10:11]
	v_pk_fma_f32 v[4:5], v[32:33], v[4:5], v[12:13]
	s_cbranch_vccnz .LBB0_840
	v_add_co_u32_e32 v10, vcc, 0x1000, v118
	s_nop 1
	v_addc_co_u32_e32 v11, vcc, 0, v119, vcc
	global_store_dwordx4 v[10:11], v[6:9], off offset:1024
	s_and_saveexec_b64 s[0:1], s[38:39]
	s_cbranch_execz .LBB0_839
	v_add_co_u32_e32 v10, vcc, 0x1000, v104
	s_nop 1
	v_addc_co_u32_e32 v11, vcc, 0, v105, vcc
	global_store_dwordx4 v[10:11], v[2:5], off offset:1024

; __device__ __forceinline__ unsigned pk2(float lo, float hi) { return f2bf(lo) | (f2bf(hi) << 16); }
; __device__ __forceinline__ void ln_phase(const Params& p, const int layer, const int row_lo, const int row_hi, const int wg_id, const int n_wg) {
;     ...
;         for (int j = 0; j < 8; ++j) { const f32x4 gv = *((const f32x4*)g + lane + 64 * j), bv = *((const f32x4*)bb + lane + 64 * j);
;             const f32x4 y0 = v0[j] * rstd0 * gv + bv, y1 = v1[j] * rstd1 * gv + bv;
;             if (layer == 0) { o80[64 * j] = (unsigned long long)pk2(y0.x, y0.y) | ((unsigned long long)pk2(y0.z, y0.w) << 32);
;                 if (ok1) o81[64 * j] = (unsigned long long)pk2(y1.x, y1.y) | ((unsigned long long)pk2(y1.z, y1.w) << 32); }
;             else { zr0[64 * j] = y0; if (ok1) zr1[64 * j] = y1; } }
.LBB0_844:
	v_mov_b64_e32 v[2:3], v[236:237]
	v_mov_b64_e32 v[4:5], v[238:239]
	v_mov_b64_e32 v[10:11], v[86:87]
	v_mov_b64_e32 v[12:13], v[88:89]
	v_mov_b32_e32 v6, v120
	v_mov_b32_e32 v7, v120
	v_pk_mul_f32 v[6:7], v[28:29], v[6:7]
	v_pk_mul_f32 v[26:27], v[26:27], v[120:121]
	v_pk_mul_f32 v[22:23], v[22:23], v[122:123]
	s_mov_b64 s[0:1], -1
	s_and_b64 vcc, exec, s[40:41]
	v_pk_fma_f32 v[8:9], v[6:7], v[4:5], v[12:13]
	v_pk_fma_f32 v[6:7], v[26:27], v[2:3], v[10:11]
	v_mov_b32_e32 v26, v122
	v_mov_b32_e32 v27, v122
	v_pk_mul_f32 v[24:25], v[24:25], v[26:27]
	v_pk_fma_f32 v[2:3], v[22:23], v[2:3], v[10:11]
	v_pk_fma_f32 v[4:5], v[24:25], v[4:5], v[12:13]
	s_cbranch_vccnz .LBB0_848
	v_add_co_u32_e32 v10, vcc, 0x1000, v118
	s_nop 1
	v_addc_co_u32_e32 v11, vcc, 0, v119, vcc
	global_store_dwordx4 v[10:11], v[6:9], off offset:2048
	s_and_saveexec_b64 s[0:1], s[38:39]
	s_cbranch_execz .LBB0_847
	v_add_co_u32_e32 v10, vcc, 0x1000, v104
	s_nop 1
	v_addc_co_u32_e32 v11, vcc, 0, v105, vcc
	global_store_dwordx4 v[10:11], v[2:5], off offset:2048

; __device__ __forceinline__ unsigned pk2(float lo, float hi) { return f2bf(lo) | (f2bf(hi) << 16); }
; __device__ __forceinline__ void ln_phase(const Params& p, const int layer, const int row_lo, const int row_hi, const int wg_id, const int n_wg) {
;     ...
;         for (int j = 0; j < 8; ++j) { const f32x4 gv = *((const f32x4*)g + lane + 64 * j), bv = *((const f32x4*)bb + lane + 64 * j);
;             const f32x4 y0 = v0[j] * rstd0 * gv + bv, y1 = v1[j] * rstd1 * gv + bv;
;             if (layer == 0) { o80[64 * j] = (unsigned long long)pk2(y0.x, y0.y) | ((unsigned long long)pk2(y0.z, y0.w) << 32);
;                 if (ok1) o81[64 * j] = (unsigned long long)pk2(y1.x, y1.y) | ((unsigned long long)pk2(y1.z, y1.w) << 32); }
;             else { zr0[64 * j] = y0; if (ok1) zr1[64 * j] = y1; } }
.LBB0_852:
	v_mov_b64_e32 v[2:3], v[244:245]
	v_mov_b64_e32 v[4:5], v[246:247]
	v_mov_b64_e32 v[10:11], v[90:91]
	v_mov_b64_e32 v[12:13], v[92:93]
	v_mov_b32_e32 v6, v120
	v_mov_b32_e32 v7, v120
	v_mov_b32_e32 v8, v122
	v_mov_b32_e32 v9, v122
	v_pk_mul_f32 v[20:21], v[20:21], v[120:121]
	v_pk_mul_f32 v[18:19], v[18:19], v[122:123]
	v_pk_mul_f32 v[6:7], v[14:15], v[6:7]
	v_pk_mul_f32 v[14:15], v[16:17], v[8:9]
	s_and_b64 vcc, exec, s[40:41]
	s_mov_b64 s[0:1], -1
	v_pk_fma_f32 v[8:9], v[6:7], v[4:5], v[12:13]
	v_pk_fma_f32 v[6:7], v[20:21], v[2:3], v[10:11]
	v_pk_fma_f32 v[4:5], v[14:15], v[4:5], v[12:13]
	v_pk_fma_f32 v[2:3], v[18:19], v[2:3], v[10:11]
	s_cbranch_vccnz .LBB0_856
	v_add_co_u32_e32 v10, vcc, 0x1000, v118
	s_nop 1
	v_addc_co_u32_e32 v11, vcc, 0, v119, vcc
	global_store_dwordx4 v[10:11], v[6:9], off offset:3072
	s_and_saveexec_b64 s[0:1], s[38:39]
	s_cbranch_execz .LBB0_855
	v_add_co_u32_e32 v10, vcc, 0x1000, v104
	s_nop 1
	v_addc_co_u32_e32 v11, vcc, 0, v105, vcc
	global_store_dwordx4 v[10:11], v[2:5], off offset:3072
